# loop-edge edit (7.11 variant): the K-loop counter/pointer SALU block of all seven GEMM mainloops moved in front of the loop-back barrier; only the branch follows the barrier
# baseline (speedup 1.0000x reference)
.LBB0_138:
	ds_read_b128 v[56:59], v178
	ds_read_b128 v[60:63], v178 offset:1024
	ds_read_b128 v[72:75], v178 offset:2048
	ds_read_b128 v[76:79], v178 offset:3072
	ds_read_b128 v[166:169], v179
	ds_read_b128 v[170:173], v179 offset:1024
	ds_read_b128 v[182:185], v179 offset:2048
	ds_read_b128 v[186:189], v179 offset:3072
	s_add_u32 s56, s52, 0xfffc0080
	s_addc_u32 s57, s53, -1
	s_cmp_eq_u32 s63, 12
	s_cselect_b32 s59, s3, s57
	s_cselect_b32 s58, s55, s56
	s_cselect_b32 s57, s17, s62
	s_cselect_b32 s56, s60, s61
	v_lshl_add_u64 v[174:175], s[52:53], 0, v[156:157]
	s_add_i32 m0, s64, 0xc000
	ds_read_b128 v[190:193], v180
	ds_read_b128 v[194:197], v180 offset:1024
	ds_read_b128 v[198:201], v180 offset:2048
	ds_read_b128 v[202:205], v180 offset:3072
	ds_read_b128 v[206:209], v180 offset:4096
	ds_read_b128 v[212:215], v180 offset:5120
	ds_read_b128 v[216:219], v180 offset:6144
	ds_read_b128 v[220:223], v180 offset:7168
	global_load_lds_dwordx4 v[174:175], off
	v_lshl_add_u64 v[174:175], s[52:53], 0, v[158:159]
	s_add_i32 m0, s64, 0xe000
	s_nop 0
	global_load_lds_dwordx4 v[174:175], off
	s_waitcnt vmcnt(8)
	s_waitcnt lgkmcnt(0)
	s_barrier
	s_setprio 1
	s_waitcnt lgkmcnt(0)
	v_mfma_f32_16x16x32_bf16 v[140:143], v[56:59], v[190:193], v[140:143]
	v_mfma_f32_16x16x32_bf16 v[136:139], v[72:75], v[190:193], v[136:139]
	v_mfma_f32_16x16x32_bf16 v[124:127], v[56:59], v[198:201], v[124:127]
	v_mfma_f32_16x16x32_bf16 v[120:123], v[72:75], v[198:201], v[120:123]
	v_mfma_f32_16x16x32_bf16 v[108:111], v[56:59], v[206:209], v[108:111]
	v_mfma_f32_16x16x32_bf16 v[104:107], v[72:75], v[206:209], v[104:107]
	v_mfma_f32_16x16x32_bf16 v[92:95], v[56:59], v[216:219], v[92:95]
	v_mfma_f32_16x16x32_bf16 v[88:91], v[72:75], v[216:219], v[88:91]
	v_mfma_f32_16x16x32_bf16 v[140:143], v[60:63], v[194:197], v[140:143]
	v_mfma_f32_16x16x32_bf16 v[136:139], v[76:79], v[194:197], v[136:139]
	v_mfma_f32_16x16x32_bf16 v[124:127], v[60:63], v[202:205], v[124:127]
	v_mfma_f32_16x16x32_bf16 v[120:123], v[76:79], v[202:205], v[120:123]
	v_mfma_f32_16x16x32_bf16 v[108:111], v[60:63], v[212:215], v[108:111]
	v_mfma_f32_16x16x32_bf16 v[104:107], v[76:79], v[212:215], v[104:107]
	v_mfma_f32_16x16x32_bf16 v[92:95], v[60:63], v[220:223], v[92:95]
	v_mfma_f32_16x16x32_bf16 v[88:91], v[76:79], v[220:223], v[88:91]
	s_setprio 0
	s_setprio 1
	v_mfma_f32_16x16x32_bf16 v[132:135], v[166:169], v[190:193], v[132:135]
	v_mfma_f32_16x16x32_bf16 v[128:131], v[182:185], v[190:193], v[128:131]
	v_mfma_f32_16x16x32_bf16 v[116:119], v[166:169], v[198:201], v[116:119]
	v_mfma_f32_16x16x32_bf16 v[112:115], v[182:185], v[198:201], v[112:115]
	v_mfma_f32_16x16x32_bf16 v[100:103], v[166:169], v[206:209], v[100:103]
	v_mfma_f32_16x16x32_bf16 v[96:99], v[182:185], v[206:209], v[96:99]
	v_mfma_f32_16x16x32_bf16 v[84:87], v[166:169], v[216:219], v[84:87]
	v_mfma_f32_16x16x32_bf16 v[80:83], v[182:185], v[216:219], v[80:83]
	v_mfma_f32_16x16x32_bf16 v[132:135], v[170:173], v[194:197], v[132:135]
	v_mfma_f32_16x16x32_bf16 v[128:131], v[186:189], v[194:197], v[128:131]
	v_mfma_f32_16x16x32_bf16 v[116:119], v[170:173], v[202:205], v[116:119]
	v_mfma_f32_16x16x32_bf16 v[112:115], v[186:189], v[202:205], v[112:115]
	v_mfma_f32_16x16x32_bf16 v[100:103], v[170:173], v[212:215], v[100:103]
	v_mfma_f32_16x16x32_bf16 v[96:99], v[186:189], v[212:215], v[96:99]
	v_mfma_f32_16x16x32_bf16 v[84:87], v[170:173], v[220:223], v[84:87]
	v_mfma_f32_16x16x32_bf16 v[80:83], v[186:189], v[220:223], v[80:83]
	s_setprio 0
	s_barrier
	s_add_i32 s81, s14, s35
	v_lshl_add_u64 v[174:175], s[56:57], 0, v[146:147]
	s_mov_b32 m0, s81
	ds_read_b128 v[190:193], v180 offset:16384
	ds_read_b128 v[194:197], v180 offset:17408
	ds_read_b128 v[198:201], v180 offset:18432
	ds_read_b128 v[202:205], v180 offset:19456
	ds_read_b128 v[206:209], v180 offset:20480
	ds_read_b128 v[212:215], v180 offset:21504
	ds_read_b128 v[216:219], v180 offset:22528
	ds_read_b128 v[220:223], v180 offset:23552
	global_load_lds_dwordx4 v[174:175], off
	s_add_i32 m0, s81, 0x2000
	s_add_u32 vcc_lo, s56, 0x40000
	v_lshl_add_u64 v[224:225], s[56:57], 0, v[150:151]
	s_addc_u32 vcc_hi, s57, 0
	s_add_i32 s81, s15, s35
	global_load_lds_dwordx4 v[224:225], off
	v_lshl_add_u64 v[226:227], vcc, 0, v[146:147]
	s_mov_b32 m0, s81
	v_lshl_add_u64 v[228:229], s[58:59], 0, v[148:149]
	global_load_lds_dwordx4 v[226:227], off
	v_lshl_add_u64 v[226:227], vcc, 0, v[150:151]
	s_add_i32 m0, s81, 0x2000
	s_nop 0
	global_load_lds_dwordx4 v[226:227], off
	v_lshl_add_u64 v[226:227], s[58:59], 0, v[144:145]
	s_mov_b32 m0, s64
	s_nop 0
	global_load_lds_dwordx4 v[226:227], off
	s_mov_b32 m0, s65
	s_nop 0
	global_load_lds_dwordx4 v[228:229], off
	s_waitcnt vmcnt(8)
	s_waitcnt lgkmcnt(0)
	s_barrier
	s_setprio 1
	s_waitcnt lgkmcnt(0)
	v_mfma_f32_16x16x32_bf16 v[68:71], v[56:59], v[190:193], v[68:71]
	v_mfma_f32_16x16x32_bf16 v[64:67], v[72:75], v[190:193], v[64:67]
	v_mfma_f32_16x16x32_bf16 v[44:47], v[56:59], v[198:201], v[44:47]
	v_mfma_f32_16x16x32_bf16 v[40:43], v[72:75], v[198:201], v[40:43]
	v_mfma_f32_16x16x32_bf16 v[28:31], v[56:59], v[206:209], v[28:31]
	v_mfma_f32_16x16x32_bf16 v[24:27], v[72:75], v[206:209], v[24:27]
	v_mfma_f32_16x16x32_bf16 v[12:15], v[56:59], v[216:219], v[12:15]
	v_mfma_f32_16x16x32_bf16 v[8:11], v[72:75], v[216:219], v[8:11]
	v_mfma_f32_16x16x32_bf16 v[68:71], v[60:63], v[194:197], v[68:71]
	v_mfma_f32_16x16x32_bf16 v[64:67], v[76:79], v[194:197], v[64:67]
	v_mfma_f32_16x16x32_bf16 v[44:47], v[60:63], v[202:205], v[44:47]
	v_mfma_f32_16x16x32_bf16 v[40:43], v[76:79], v[202:205], v[40:43]
	v_mfma_f32_16x16x32_bf16 v[28:31], v[60:63], v[212:215], v[28:31]
	v_mfma_f32_16x16x32_bf16 v[24:27], v[76:79], v[212:215], v[24:27]
	v_mfma_f32_16x16x32_bf16 v[12:15], v[60:63], v[220:223], v[12:15]
	v_mfma_f32_16x16x32_bf16 v[8:11], v[76:79], v[220:223], v[8:11]
	s_setprio 0
	s_setprio 1
	v_mfma_f32_16x16x32_bf16 v[52:55], v[166:169], v[190:193], v[52:55]
	v_mfma_f32_16x16x32_bf16 v[48:51], v[182:185], v[190:193], v[48:51]
	v_mfma_f32_16x16x32_bf16 v[36:39], v[166:169], v[198:201], v[36:39]
	v_mfma_f32_16x16x32_bf16 v[32:35], v[182:185], v[198:201], v[32:35]
	v_mfma_f32_16x16x32_bf16 v[20:23], v[166:169], v[206:209], v[20:23]
	v_mfma_f32_16x16x32_bf16 v[16:19], v[182:185], v[206:209], v[16:19]
	v_mfma_f32_16x16x32_bf16 v[4:7], v[166:169], v[216:219], v[4:7]
	v_mfma_f32_16x16x32_bf16 v[0:3], v[182:185], v[216:219], v[0:3]
	v_mfma_f32_16x16x32_bf16 v[52:55], v[170:173], v[194:197], v[52:55]
	v_mfma_f32_16x16x32_bf16 v[48:51], v[186:189], v[194:197], v[48:51]
	v_mfma_f32_16x16x32_bf16 v[36:39], v[170:173], v[202:205], v[36:39]
	v_mfma_f32_16x16x32_bf16 v[32:35], v[186:189], v[202:205], v[32:35]
	v_mfma_f32_16x16x32_bf16 v[20:23], v[170:173], v[212:215], v[20:23]
	v_mfma_f32_16x16x32_bf16 v[16:19], v[186:189], v[212:215], v[16:19]
	v_mfma_f32_16x16x32_bf16 v[4:7], v[170:173], v[220:223], v[4:7]
	v_mfma_f32_16x16x32_bf16 v[0:3], v[186:189], v[220:223], v[0:3]
	s_setprio 0
	s_barrier
	s_add_i32 s81, 0, 0x18000
	s_add_i32 vcc_lo, 0, 0x1c000
	v_add_u32_e32 v76, s81, v177
	v_add_u32_e32 v186, vcc_lo, v177
	ds_read_b128 v[56:59], v76
	ds_read_b128 v[60:63], v76 offset:1024
	ds_read_b128 v[72:75], v76 offset:2048
	ds_read_b128 v[76:79], v76 offset:3072
	ds_read_b128 v[166:169], v186
	ds_read_b128 v[170:173], v186 offset:1024
	ds_read_b128 v[182:185], v186 offset:2048
	ds_read_b128 v[186:189], v186 offset:3072
	s_add_u32 s58, s58, 0x40000
	s_addc_u32 s59, s59, 0
	s_mov_b32 m0, s66
	v_lshl_add_u64 v[230:231], s[58:59], 0, v[144:145]
	ds_read_b128 v[190:193], v180 offset:32768
	ds_read_b128 v[194:197], v180 offset:33792
	ds_read_b128 v[198:201], v180 offset:34816
	ds_read_b128 v[202:205], v180 offset:35840
	ds_read_b128 v[206:209], v180 offset:36864
	ds_read_b128 v[212:215], v180 offset:37888
	ds_read_b128 v[216:219], v180 offset:38912
	ds_read_b128 v[220:223], v180 offset:39936
	global_load_lds_dwordx4 v[230:231], off
	v_lshl_add_u64 v[230:231], s[58:59], 0, v[148:149]
	s_mov_b32 m0, s67
	s_nop 0
	global_load_lds_dwordx4 v[230:231], off
	s_waitcnt vmcnt(8)
	s_waitcnt lgkmcnt(0)
	s_barrier
	s_setprio 1
	s_waitcnt lgkmcnt(0)
	v_mfma_f32_16x16x32_bf16 v[140:143], v[56:59], v[190:193], v[140:143]
	v_mfma_f32_16x16x32_bf16 v[136:139], v[72:75], v[190:193], v[136:139]
	v_mfma_f32_16x16x32_bf16 v[124:127], v[56:59], v[198:201], v[124:127]
	v_mfma_f32_16x16x32_bf16 v[120:123], v[72:75], v[198:201], v[120:123]
	v_mfma_f32_16x16x32_bf16 v[108:111], v[56:59], v[206:209], v[108:111]
	v_mfma_f32_16x16x32_bf16 v[104:107], v[72:75], v[206:209], v[104:107]
	v_mfma_f32_16x16x32_bf16 v[92:95], v[56:59], v[216:219], v[92:95]
	v_mfma_f32_16x16x32_bf16 v[88:91], v[72:75], v[216:219], v[88:91]
	v_mfma_f32_16x16x32_bf16 v[140:143], v[60:63], v[194:197], v[140:143]
	v_mfma_f32_16x16x32_bf16 v[136:139], v[76:79], v[194:197], v[136:139]
	v_mfma_f32_16x16x32_bf16 v[124:127], v[60:63], v[202:205], v[124:127]
	v_mfma_f32_16x16x32_bf16 v[120:123], v[76:79], v[202:205], v[120:123]
	v_mfma_f32_16x16x32_bf16 v[108:111], v[60:63], v[212:215], v[108:111]
	v_mfma_f32_16x16x32_bf16 v[104:107], v[76:79], v[212:215], v[104:107]
	v_mfma_f32_16x16x32_bf16 v[92:95], v[60:63], v[220:223], v[92:95]
	v_mfma_f32_16x16x32_bf16 v[88:91], v[76:79], v[220:223], v[88:91]
	s_setprio 0
	s_setprio 1
	v_mfma_f32_16x16x32_bf16 v[132:135], v[166:169], v[190:193], v[132:135]
	v_mfma_f32_16x16x32_bf16 v[128:131], v[182:185], v[190:193], v[128:131]
	v_mfma_f32_16x16x32_bf16 v[116:119], v[166:169], v[198:201], v[116:119]
	v_mfma_f32_16x16x32_bf16 v[112:115], v[182:185], v[198:201], v[112:115]
	v_mfma_f32_16x16x32_bf16 v[100:103], v[166:169], v[206:209], v[100:103]
	v_mfma_f32_16x16x32_bf16 v[96:99], v[182:185], v[206:209], v[96:99]
	v_mfma_f32_16x16x32_bf16 v[84:87], v[166:169], v[216:219], v[84:87]
	v_mfma_f32_16x16x32_bf16 v[80:83], v[182:185], v[216:219], v[80:83]
	v_mfma_f32_16x16x32_bf16 v[132:135], v[170:173], v[194:197], v[132:135]
	v_mfma_f32_16x16x32_bf16 v[128:131], v[186:189], v[194:197], v[128:131]
	v_mfma_f32_16x16x32_bf16 v[116:119], v[170:173], v[202:205], v[116:119]
	v_mfma_f32_16x16x32_bf16 v[112:115], v[186:189], v[202:205], v[112:115]
	v_mfma_f32_16x16x32_bf16 v[100:103], v[170:173], v[212:215], v[100:103]
	v_mfma_f32_16x16x32_bf16 v[96:99], v[186:189], v[212:215], v[96:99]
	v_mfma_f32_16x16x32_bf16 v[84:87], v[170:173], v[220:223], v[84:87]
	v_mfma_f32_16x16x32_bf16 v[80:83], v[186:189], v[220:223], v[80:83]
	s_setprio 0
	s_barrier
	s_add_i32 s58, s81, s35
	v_lshl_add_u64 v[174:175], v[174:175], 0, s[76:77]
	s_mov_b32 m0, s58
	ds_read_b128 v[190:193], v180 offset:49152
	ds_read_b128 v[194:197], v180 offset:50176
	ds_read_b128 v[198:201], v180 offset:51200
	ds_read_b128 v[202:205], v180 offset:52224
	ds_read_b128 v[206:209], v180 offset:53248
	ds_read_b128 v[212:215], v180 offset:54272
	ds_read_b128 v[216:219], v180 offset:55296
	ds_read_b128 v[220:223], v180 offset:56320
	global_load_lds_dwordx4 v[174:175], off
	s_add_i32 m0, s58, 0x2000
	s_add_u32 s56, s56, 0x40080
	v_lshl_add_u64 v[174:175], v[224:225], 0, s[76:77]
	s_addc_u32 s57, s57, 0
	s_add_i32 s58, vcc_lo, s35
	global_load_lds_dwordx4 v[174:175], off
	v_lshl_add_u64 v[174:175], s[56:57], 0, v[146:147]
	s_mov_b32 m0, s58
	s_nop 0
	global_load_lds_dwordx4 v[174:175], off
	v_lshl_add_u64 v[174:175], s[56:57], 0, v[150:151]
	s_add_i32 m0, s58, 0x2000
	s_nop 0
	global_load_lds_dwordx4 v[174:175], off
	v_lshl_add_u64 v[174:175], v[226:227], 0, s[76:77]
	s_mov_b32 m0, s4
	s_nop 0
	global_load_lds_dwordx4 v[174:175], off
	v_lshl_add_u64 v[174:175], v[228:229], 0, s[76:77]
	s_mov_b32 m0, s5
	s_nop 0
	global_load_lds_dwordx4 v[174:175], off
	s_waitcnt vmcnt(8)
	s_waitcnt lgkmcnt(0)
	s_barrier
	s_setprio 1
	s_waitcnt lgkmcnt(0)
	v_mfma_f32_16x16x32_bf16 v[68:71], v[56:59], v[190:193], v[68:71]
	v_mfma_f32_16x16x32_bf16 v[64:67], v[72:75], v[190:193], v[64:67]
	v_mfma_f32_16x16x32_bf16 v[44:47], v[56:59], v[198:201], v[44:47]
	v_mfma_f32_16x16x32_bf16 v[40:43], v[72:75], v[198:201], v[40:43]
	v_mfma_f32_16x16x32_bf16 v[28:31], v[56:59], v[206:209], v[28:31]
	v_mfma_f32_16x16x32_bf16 v[24:27], v[72:75], v[206:209], v[24:27]
	v_mfma_f32_16x16x32_bf16 v[12:15], v[56:59], v[216:219], v[12:15]
	v_mfma_f32_16x16x32_bf16 v[8:11], v[72:75], v[216:219], v[8:11]
	v_mfma_f32_16x16x32_bf16 v[68:71], v[60:63], v[194:197], v[68:71]
	v_mfma_f32_16x16x32_bf16 v[64:67], v[76:79], v[194:197], v[64:67]
	v_mfma_f32_16x16x32_bf16 v[44:47], v[60:63], v[202:205], v[44:47]
	v_mfma_f32_16x16x32_bf16 v[40:43], v[76:79], v[202:205], v[40:43]
	v_mfma_f32_16x16x32_bf16 v[28:31], v[60:63], v[212:215], v[28:31]
	v_mfma_f32_16x16x32_bf16 v[24:27], v[76:79], v[212:215], v[24:27]
	v_mfma_f32_16x16x32_bf16 v[12:15], v[60:63], v[220:223], v[12:15]
	v_mfma_f32_16x16x32_bf16 v[8:11], v[76:79], v[220:223], v[8:11]
	s_setprio 0
	s_setprio 1
	v_mfma_f32_16x16x32_bf16 v[52:55], v[166:169], v[190:193], v[52:55]
	v_mfma_f32_16x16x32_bf16 v[48:51], v[182:185], v[190:193], v[48:51]
	v_mfma_f32_16x16x32_bf16 v[36:39], v[166:169], v[198:201], v[36:39]
	v_mfma_f32_16x16x32_bf16 v[32:35], v[182:185], v[198:201], v[32:35]
	v_mfma_f32_16x16x32_bf16 v[20:23], v[166:169], v[206:209], v[20:23]
	v_mfma_f32_16x16x32_bf16 v[16:19], v[182:185], v[206:209], v[16:19]
	v_mfma_f32_16x16x32_bf16 v[4:7], v[166:169], v[216:219], v[4:7]
	v_mfma_f32_16x16x32_bf16 v[0:3], v[182:185], v[216:219], v[0:3]
	v_mfma_f32_16x16x32_bf16 v[52:55], v[170:173], v[194:197], v[52:55]
	v_mfma_f32_16x16x32_bf16 v[48:51], v[186:189], v[194:197], v[48:51]
	v_mfma_f32_16x16x32_bf16 v[36:39], v[170:173], v[202:205], v[36:39]
	v_mfma_f32_16x16x32_bf16 v[32:35], v[186:189], v[202:205], v[32:35]
	v_mfma_f32_16x16x32_bf16 v[20:23], v[170:173], v[212:215], v[20:23]
	v_mfma_f32_16x16x32_bf16 v[16:19], v[186:189], v[212:215], v[16:19]
	v_mfma_f32_16x16x32_bf16 v[4:7], v[170:173], v[220:223], v[4:7]
	v_mfma_f32_16x16x32_bf16 v[0:3], v[186:189], v[220:223], v[0:3]
	s_add_i32 s63, s63, 2
	s_add_u32 s52, s52, 0x100
	s_addc_u32 s53, s53, 0
	s_add_u32 s61, s61, 0x100
	s_addc_u32 s62, s62, 0
	s_cmp_gt_u32 s63, 13
	s_setprio 0
	s_barrier
	s_cbranch_scc0 .LBB0_138
	s_and_b64 vcc, exec, s[78:79]
	s_cbranch_vccz .LBB0_141
	s_barrier

.LBB0_488:
	s_waitcnt vmcnt(0)
	ds_read_b128 v[64:67], v172
	ds_read_b128 v[68:71], v172 offset:1024
	ds_read_b128 v[72:75], v172 offset:2048
	ds_read_b128 v[76:79], v172 offset:3072
	ds_read_b128 v[166:169], v173
	ds_read_b128 v[176:179], v173 offset:1024
	ds_read_b128 v[182:185], v173 offset:2048
	ds_read_b128 v[186:189], v173 offset:3072
	s_add_u32 s28, s2, 0xfffe8080
	s_addc_u32 s29, s3, -1
	s_cmp_eq_u32 s53, 2
	s_cselect_b32 s39, s21, s29
	s_cselect_b32 s38, s20, s28
	s_cselect_b32 s29, s23, s52
	s_cselect_b32 s28, s22, s49
	v_lshl_add_u64 v[170:171], s[2:3], 0, v[156:157]
	s_add_i32 m0, s35, 0xc000
	ds_read_b128 v[190:193], v174
	ds_read_b128 v[194:197], v174 offset:1024
	ds_read_b128 v[198:201], v174 offset:2048
	ds_read_b128 v[202:205], v174 offset:3072
	ds_read_b128 v[206:209], v174 offset:4096
	ds_read_b128 v[212:215], v174 offset:5120
	ds_read_b128 v[216:219], v174 offset:6144
	ds_read_b128 v[220:223], v174 offset:7168
	global_load_lds_dwordx4 v[170:171], off
	v_lshl_add_u64 v[170:171], s[2:3], 0, v[158:159]
	s_add_i32 m0, s35, 0xe000
	s_nop 0
	global_load_lds_dwordx4 v[170:171], off
	s_waitcnt vmcnt(8)
	s_waitcnt lgkmcnt(0)
	s_barrier
	s_setprio 1
	s_waitcnt lgkmcnt(0)
	v_mfma_f32_16x16x32_bf16 v[140:143], v[64:67], v[190:193], v[140:143]
	v_mfma_f32_16x16x32_bf16 v[136:139], v[72:75], v[190:193], v[136:139]
	v_mfma_f32_16x16x32_bf16 v[124:127], v[64:67], v[198:201], v[124:127]
	v_mfma_f32_16x16x32_bf16 v[120:123], v[72:75], v[198:201], v[120:123]
	v_mfma_f32_16x16x32_bf16 v[108:111], v[64:67], v[206:209], v[108:111]
	v_mfma_f32_16x16x32_bf16 v[104:107], v[72:75], v[206:209], v[104:107]
	v_mfma_f32_16x16x32_bf16 v[92:95], v[64:67], v[216:219], v[92:95]
	v_mfma_f32_16x16x32_bf16 v[88:91], v[72:75], v[216:219], v[88:91]
	v_mfma_f32_16x16x32_bf16 v[140:143], v[68:71], v[194:197], v[140:143]
	v_mfma_f32_16x16x32_bf16 v[136:139], v[76:79], v[194:197], v[136:139]
	v_mfma_f32_16x16x32_bf16 v[124:127], v[68:71], v[202:205], v[124:127]
	v_mfma_f32_16x16x32_bf16 v[120:123], v[76:79], v[202:205], v[120:123]
	v_mfma_f32_16x16x32_bf16 v[108:111], v[68:71], v[212:215], v[108:111]
	v_mfma_f32_16x16x32_bf16 v[104:107], v[76:79], v[212:215], v[104:107]
	v_mfma_f32_16x16x32_bf16 v[92:95], v[68:71], v[220:223], v[92:95]
	v_mfma_f32_16x16x32_bf16 v[88:91], v[76:79], v[220:223], v[88:91]
	s_setprio 0
	s_setprio 1
	v_mfma_f32_16x16x32_bf16 v[132:135], v[166:169], v[190:193], v[132:135]
	v_mfma_f32_16x16x32_bf16 v[128:131], v[182:185], v[190:193], v[128:131]
	v_mfma_f32_16x16x32_bf16 v[116:119], v[166:169], v[198:201], v[116:119]
	v_mfma_f32_16x16x32_bf16 v[112:115], v[182:185], v[198:201], v[112:115]
	v_mfma_f32_16x16x32_bf16 v[100:103], v[166:169], v[206:209], v[100:103]
	v_mfma_f32_16x16x32_bf16 v[96:99], v[182:185], v[206:209], v[96:99]
	v_mfma_f32_16x16x32_bf16 v[84:87], v[166:169], v[216:219], v[84:87]
	v_mfma_f32_16x16x32_bf16 v[80:83], v[182:185], v[216:219], v[80:83]
	v_mfma_f32_16x16x32_bf16 v[132:135], v[176:179], v[194:197], v[132:135]
	v_mfma_f32_16x16x32_bf16 v[128:131], v[186:189], v[194:197], v[128:131]
	v_mfma_f32_16x16x32_bf16 v[116:119], v[176:179], v[202:205], v[116:119]
	v_mfma_f32_16x16x32_bf16 v[112:115], v[186:189], v[202:205], v[112:115]
	v_mfma_f32_16x16x32_bf16 v[100:103], v[176:179], v[212:215], v[100:103]
	v_mfma_f32_16x16x32_bf16 v[96:99], v[186:189], v[212:215], v[96:99]
	v_mfma_f32_16x16x32_bf16 v[84:87], v[176:179], v[220:223], v[84:87]
	v_mfma_f32_16x16x32_bf16 v[80:83], v[186:189], v[220:223], v[80:83]
	s_setprio 0
	s_barrier
	s_add_i32 s76, s63, s11
	v_lshl_add_u64 v[170:171], s[28:29], 0, v[146:147]
	s_mov_b32 m0, s76
	ds_read_b128 v[190:193], v174 offset:16384
	ds_read_b128 v[194:197], v174 offset:17408
	ds_read_b128 v[198:201], v174 offset:18432
	ds_read_b128 v[202:205], v174 offset:19456
	ds_read_b128 v[206:209], v174 offset:20480
	ds_read_b128 v[212:215], v174 offset:21504
	ds_read_b128 v[216:219], v174 offset:22528
	ds_read_b128 v[220:223], v174 offset:23552
	global_load_lds_dwordx4 v[170:171], off
	s_add_i32 m0, s76, 0x2000
	s_add_u32 s76, s28, 0x18000
	v_lshl_add_u64 v[224:225], s[28:29], 0, v[150:151]
	s_addc_u32 s77, s29, 0
	s_add_i32 s78, s64, s11
	global_load_lds_dwordx4 v[224:225], off
	v_lshl_add_u64 v[226:227], s[76:77], 0, v[146:147]
	s_mov_b32 m0, s78
	v_lshl_add_u64 v[228:229], s[38:39], 0, v[148:149]
	global_load_lds_dwordx4 v[226:227], off
	v_lshl_add_u64 v[226:227], s[76:77], 0, v[150:151]
	s_add_i32 m0, s78, 0x2000
	s_nop 0
	global_load_lds_dwordx4 v[226:227], off
	v_lshl_add_u64 v[226:227], s[38:39], 0, v[144:145]
	s_mov_b32 m0, s35
	s_nop 0
	global_load_lds_dwordx4 v[226:227], off
	s_mov_b32 m0, s54
	s_nop 0
	global_load_lds_dwordx4 v[228:229], off
	s_waitcnt vmcnt(8)
	s_waitcnt lgkmcnt(0)
	s_barrier
	s_setprio 1
	s_waitcnt lgkmcnt(0)
	v_mfma_f32_16x16x32_bf16 v[60:63], v[64:67], v[190:193], v[60:63]
	v_mfma_f32_16x16x32_bf16 v[56:59], v[72:75], v[190:193], v[56:59]
	v_mfma_f32_16x16x32_bf16 v[44:47], v[64:67], v[198:201], v[44:47]
	v_mfma_f32_16x16x32_bf16 v[40:43], v[72:75], v[198:201], v[40:43]
	v_mfma_f32_16x16x32_bf16 v[28:31], v[64:67], v[206:209], v[28:31]
	v_mfma_f32_16x16x32_bf16 v[24:27], v[72:75], v[206:209], v[24:27]
	v_mfma_f32_16x16x32_bf16 v[12:15], v[64:67], v[216:219], v[12:15]
	v_mfma_f32_16x16x32_bf16 v[8:11], v[72:75], v[216:219], v[8:11]
	v_mfma_f32_16x16x32_bf16 v[60:63], v[68:71], v[194:197], v[60:63]
	v_mfma_f32_16x16x32_bf16 v[56:59], v[76:79], v[194:197], v[56:59]
	v_mfma_f32_16x16x32_bf16 v[44:47], v[68:71], v[202:205], v[44:47]
	v_mfma_f32_16x16x32_bf16 v[40:43], v[76:79], v[202:205], v[40:43]
	v_mfma_f32_16x16x32_bf16 v[28:31], v[68:71], v[212:215], v[28:31]
	v_mfma_f32_16x16x32_bf16 v[24:27], v[76:79], v[212:215], v[24:27]
	v_mfma_f32_16x16x32_bf16 v[12:15], v[68:71], v[220:223], v[12:15]
	v_mfma_f32_16x16x32_bf16 v[8:11], v[76:79], v[220:223], v[8:11]
	s_setprio 0
	s_setprio 1
	v_mfma_f32_16x16x32_bf16 v[52:55], v[166:169], v[190:193], v[52:55]
	v_mfma_f32_16x16x32_bf16 v[48:51], v[182:185], v[190:193], v[48:51]
	v_mfma_f32_16x16x32_bf16 v[36:39], v[166:169], v[198:201], v[36:39]
	v_mfma_f32_16x16x32_bf16 v[32:35], v[182:185], v[198:201], v[32:35]
	v_mfma_f32_16x16x32_bf16 v[20:23], v[166:169], v[206:209], v[20:23]
	v_mfma_f32_16x16x32_bf16 v[16:19], v[182:185], v[206:209], v[16:19]
	v_mfma_f32_16x16x32_bf16 v[4:7], v[166:169], v[216:219], v[4:7]
	v_mfma_f32_16x16x32_bf16 v[0:3], v[182:185], v[216:219], v[0:3]
	v_mfma_f32_16x16x32_bf16 v[52:55], v[176:179], v[194:197], v[52:55]
	v_mfma_f32_16x16x32_bf16 v[48:51], v[186:189], v[194:197], v[48:51]
	v_mfma_f32_16x16x32_bf16 v[36:39], v[176:179], v[202:205], v[36:39]
	v_mfma_f32_16x16x32_bf16 v[32:35], v[186:189], v[202:205], v[32:35]
	v_mfma_f32_16x16x32_bf16 v[20:23], v[176:179], v[212:215], v[20:23]
	v_mfma_f32_16x16x32_bf16 v[16:19], v[186:189], v[212:215], v[16:19]
	v_mfma_f32_16x16x32_bf16 v[4:7], v[176:179], v[220:223], v[4:7]
	v_mfma_f32_16x16x32_bf16 v[0:3], v[186:189], v[220:223], v[0:3]
	s_setprio 0
	s_barrier
	s_add_i32 s76, 0, 0x18000
	s_add_i32 s77, 0, 0x1c000
	v_add_u32_e32 v76, s76, v163
	v_add_u32_e32 v175, s77, v163
	ds_read_b128 v[64:67], v76
	ds_read_b128 v[68:71], v76 offset:1024
	ds_read_b128 v[72:75], v76 offset:2048
	ds_read_b128 v[76:79], v76 offset:3072
	ds_read_b128 v[166:169], v175
	ds_read_b128 v[176:179], v175 offset:1024
	ds_read_b128 v[182:185], v175 offset:2048
	ds_read_b128 v[186:189], v175 offset:3072
	s_add_u32 s38, s38, 0x18000
	s_addc_u32 s39, s39, 0
	s_mov_b32 m0, s55
	v_lshl_add_u64 v[230:231], s[38:39], 0, v[144:145]
	ds_read_b128 v[190:193], v174 offset:32768
	ds_read_b128 v[194:197], v174 offset:33792
	ds_read_b128 v[198:201], v174 offset:34816
	ds_read_b128 v[202:205], v174 offset:35840
	ds_read_b128 v[206:209], v174 offset:36864
	ds_read_b128 v[212:215], v174 offset:37888
	ds_read_b128 v[216:219], v174 offset:38912
	ds_read_b128 v[220:223], v174 offset:39936
	global_load_lds_dwordx4 v[230:231], off
	v_lshl_add_u64 v[230:231], s[38:39], 0, v[148:149]
	s_mov_b32 m0, s56
	s_nop 0
	global_load_lds_dwordx4 v[230:231], off
	s_waitcnt vmcnt(8)
	s_waitcnt lgkmcnt(0)
	s_barrier
	s_setprio 1
	s_waitcnt lgkmcnt(0)
	v_mfma_f32_16x16x32_bf16 v[140:143], v[64:67], v[190:193], v[140:143]
	v_mfma_f32_16x16x32_bf16 v[136:139], v[72:75], v[190:193], v[136:139]
	v_mfma_f32_16x16x32_bf16 v[124:127], v[64:67], v[198:201], v[124:127]
	v_mfma_f32_16x16x32_bf16 v[120:123], v[72:75], v[198:201], v[120:123]
	v_mfma_f32_16x16x32_bf16 v[108:111], v[64:67], v[206:209], v[108:111]
	v_mfma_f32_16x16x32_bf16 v[104:107], v[72:75], v[206:209], v[104:107]
	v_mfma_f32_16x16x32_bf16 v[92:95], v[64:67], v[216:219], v[92:95]
	v_mfma_f32_16x16x32_bf16 v[88:91], v[72:75], v[216:219], v[88:91]
	v_mfma_f32_16x16x32_bf16 v[140:143], v[68:71], v[194:197], v[140:143]
	v_mfma_f32_16x16x32_bf16 v[136:139], v[76:79], v[194:197], v[136:139]
	v_mfma_f32_16x16x32_bf16 v[124:127], v[68:71], v[202:205], v[124:127]
	v_mfma_f32_16x16x32_bf16 v[120:123], v[76:79], v[202:205], v[120:123]
	v_mfma_f32_16x16x32_bf16 v[108:111], v[68:71], v[212:215], v[108:111]
	v_mfma_f32_16x16x32_bf16 v[104:107], v[76:79], v[212:215], v[104:107]
	v_mfma_f32_16x16x32_bf16 v[92:95], v[68:71], v[220:223], v[92:95]
	v_mfma_f32_16x16x32_bf16 v[88:91], v[76:79], v[220:223], v[88:91]
	s_setprio 0
	s_setprio 1
	v_mfma_f32_16x16x32_bf16 v[132:135], v[166:169], v[190:193], v[132:135]
	v_mfma_f32_16x16x32_bf16 v[128:131], v[182:185], v[190:193], v[128:131]
	v_mfma_f32_16x16x32_bf16 v[116:119], v[166:169], v[198:201], v[116:119]
	v_mfma_f32_16x16x32_bf16 v[112:115], v[182:185], v[198:201], v[112:115]
	v_mfma_f32_16x16x32_bf16 v[100:103], v[166:169], v[206:209], v[100:103]
	v_mfma_f32_16x16x32_bf16 v[96:99], v[182:185], v[206:209], v[96:99]
	v_mfma_f32_16x16x32_bf16 v[84:87], v[166:169], v[216:219], v[84:87]
	v_mfma_f32_16x16x32_bf16 v[80:83], v[182:185], v[216:219], v[80:83]
	v_mfma_f32_16x16x32_bf16 v[132:135], v[176:179], v[194:197], v[132:135]
	v_mfma_f32_16x16x32_bf16 v[128:131], v[186:189], v[194:197], v[128:131]
	v_mfma_f32_16x16x32_bf16 v[116:119], v[176:179], v[202:205], v[116:119]
	v_mfma_f32_16x16x32_bf16 v[112:115], v[186:189], v[202:205], v[112:115]
	v_mfma_f32_16x16x32_bf16 v[100:103], v[176:179], v[212:215], v[100:103]
	v_mfma_f32_16x16x32_bf16 v[96:99], v[186:189], v[212:215], v[96:99]
	v_mfma_f32_16x16x32_bf16 v[84:87], v[176:179], v[220:223], v[84:87]
	v_mfma_f32_16x16x32_bf16 v[80:83], v[186:189], v[220:223], v[80:83]
	s_setprio 0
	s_barrier
	s_add_i32 s38, s76, s11
	v_lshl_add_u64 v[170:171], v[170:171], 0, s[16:17]
	s_mov_b32 m0, s38
	ds_read_b128 v[190:193], v174 offset:49152
	ds_read_b128 v[194:197], v174 offset:50176
	ds_read_b128 v[198:201], v174 offset:51200
	ds_read_b128 v[202:205], v174 offset:52224
	ds_read_b128 v[206:209], v174 offset:53248
	ds_read_b128 v[212:215], v174 offset:54272
	ds_read_b128 v[216:219], v174 offset:55296
	ds_read_b128 v[220:223], v174 offset:56320
	global_load_lds_dwordx4 v[170:171], off
	s_add_i32 m0, s38, 0x2000
	s_add_u32 s28, s28, 0x18080
	v_lshl_add_u64 v[170:171], v[224:225], 0, s[16:17]
	s_addc_u32 s29, s29, 0
	s_add_i32 s38, s77, s11
	global_load_lds_dwordx4 v[170:171], off
	v_lshl_add_u64 v[170:171], s[28:29], 0, v[146:147]
	s_mov_b32 m0, s38
	s_nop 0
	global_load_lds_dwordx4 v[170:171], off
	v_lshl_add_u64 v[170:171], s[28:29], 0, v[150:151]
	s_add_i32 m0, s38, 0x2000
	s_nop 0
	global_load_lds_dwordx4 v[170:171], off
	v_lshl_add_u64 v[170:171], v[226:227], 0, s[16:17]
	s_mov_b32 m0, s61
	s_nop 0
	global_load_lds_dwordx4 v[170:171], off
	v_lshl_add_u64 v[170:171], v[228:229], 0, s[16:17]
	s_mov_b32 m0, s62
	s_nop 0
	global_load_lds_dwordx4 v[170:171], off
	s_waitcnt vmcnt(8)
	s_waitcnt lgkmcnt(0)
	s_barrier
	s_setprio 1
	s_waitcnt lgkmcnt(0)
	v_mfma_f32_16x16x32_bf16 v[60:63], v[64:67], v[190:193], v[60:63]
	v_mfma_f32_16x16x32_bf16 v[56:59], v[72:75], v[190:193], v[56:59]
	v_mfma_f32_16x16x32_bf16 v[44:47], v[64:67], v[198:201], v[44:47]
	v_mfma_f32_16x16x32_bf16 v[40:43], v[72:75], v[198:201], v[40:43]
	v_mfma_f32_16x16x32_bf16 v[28:31], v[64:67], v[206:209], v[28:31]
	v_mfma_f32_16x16x32_bf16 v[24:27], v[72:75], v[206:209], v[24:27]
	v_mfma_f32_16x16x32_bf16 v[12:15], v[64:67], v[216:219], v[12:15]
	v_mfma_f32_16x16x32_bf16 v[8:11], v[72:75], v[216:219], v[8:11]
	v_mfma_f32_16x16x32_bf16 v[60:63], v[68:71], v[194:197], v[60:63]
	v_mfma_f32_16x16x32_bf16 v[56:59], v[76:79], v[194:197], v[56:59]
	v_mfma_f32_16x16x32_bf16 v[44:47], v[68:71], v[202:205], v[44:47]
	v_mfma_f32_16x16x32_bf16 v[40:43], v[76:79], v[202:205], v[40:43]
	v_mfma_f32_16x16x32_bf16 v[28:31], v[68:71], v[212:215], v[28:31]
	v_mfma_f32_16x16x32_bf16 v[24:27], v[76:79], v[212:215], v[24:27]
	v_mfma_f32_16x16x32_bf16 v[12:15], v[68:71], v[220:223], v[12:15]
	v_mfma_f32_16x16x32_bf16 v[8:11], v[76:79], v[220:223], v[8:11]
	s_setprio 0
	s_setprio 1
	v_mfma_f32_16x16x32_bf16 v[52:55], v[166:169], v[190:193], v[52:55]
	v_mfma_f32_16x16x32_bf16 v[48:51], v[182:185], v[190:193], v[48:51]
	v_mfma_f32_16x16x32_bf16 v[36:39], v[166:169], v[198:201], v[36:39]
	v_mfma_f32_16x16x32_bf16 v[32:35], v[182:185], v[198:201], v[32:35]
	v_mfma_f32_16x16x32_bf16 v[20:23], v[166:169], v[206:209], v[20:23]
	v_mfma_f32_16x16x32_bf16 v[16:19], v[182:185], v[206:209], v[16:19]
	v_mfma_f32_16x16x32_bf16 v[4:7], v[166:169], v[216:219], v[4:7]
	v_mfma_f32_16x16x32_bf16 v[0:3], v[182:185], v[216:219], v[0:3]
	v_mfma_f32_16x16x32_bf16 v[52:55], v[176:179], v[194:197], v[52:55]
	v_mfma_f32_16x16x32_bf16 v[48:51], v[186:189], v[194:197], v[48:51]
	v_mfma_f32_16x16x32_bf16 v[36:39], v[176:179], v[202:205], v[36:39]
	v_mfma_f32_16x16x32_bf16 v[32:35], v[186:189], v[202:205], v[32:35]
	v_mfma_f32_16x16x32_bf16 v[20:23], v[176:179], v[212:215], v[20:23]
	v_mfma_f32_16x16x32_bf16 v[16:19], v[186:189], v[212:215], v[16:19]
	v_mfma_f32_16x16x32_bf16 v[4:7], v[176:179], v[220:223], v[4:7]
	v_mfma_f32_16x16x32_bf16 v[0:3], v[186:189], v[220:223], v[0:3]
	s_add_i32 s53, s53, 2
	s_add_u32 s2, s2, 0x100
	s_addc_u32 s3, s3, 0
	s_add_u32 s49, s49, 0x100
	s_addc_u32 s52, s52, 0
	s_cmp_gt_u32 s53, 3
	s_setprio 0
	s_barrier
	s_cbranch_scc0 .LBB0_488
	s_and_b64 vcc, exec, s[18:19]
	s_cbranch_vccz .LBB0_491
	s_barrier

.LBB0_795:
	ds_read_b128 v[144:147], v160
	ds_read_b128 v[164:167], v160 offset:1024
	ds_read_b128 v[168:171], v160 offset:2048
	ds_read_b128 v[172:175], v160 offset:3072
	ds_read_b128 v[176:179], v161
	ds_read_b128 v[182:185], v161 offset:1024
	ds_read_b128 v[186:189], v161 offset:2048
	ds_read_b128 v[190:193], v161 offset:3072
	s_add_u32 s46, s44, 0xfffe0080
	s_addc_u32 s47, s45, -1
	s_cmp_eq_u32 s66, 4
	s_cselect_b32 s49, s29, s47
	s_cselect_b32 s48, s62, s46
	s_cselect_b32 s47, s23, s65
	s_cselect_b32 s46, s63, s64
	v_lshl_add_u64 v[228:229], s[44:45], 0, v[136:137]
	s_add_i32 m0, s15, 0xc000
	ds_read_b128 v[194:197], v163
	ds_read_b128 v[198:201], v163 offset:1024
	ds_read_b128 v[202:205], v163 offset:2048
	ds_read_b128 v[206:209], v163 offset:3072
	ds_read_b128 v[212:215], v163 offset:4096
	ds_read_b128 v[216:219], v163 offset:5120
	ds_read_b128 v[220:223], v163 offset:6144
	ds_read_b128 v[224:227], v163 offset:7168
	global_load_lds_dwordx4 v[228:229], off
	v_lshl_add_u64 v[228:229], s[44:45], 0, v[138:139]
	s_add_i32 m0, s15, 0xe000
	s_nop 0
	global_load_lds_dwordx4 v[228:229], off
	s_waitcnt vmcnt(8)
	s_waitcnt lgkmcnt(0)
	s_barrier
	s_setprio 1
	s_waitcnt lgkmcnt(0)
	v_mfma_f32_16x16x32_bf16 v[124:127], v[144:147], v[194:197], v[124:127]
	v_mfma_f32_16x16x32_bf16 v[120:123], v[168:171], v[194:197], v[120:123]
	v_mfma_f32_16x16x32_bf16 v[108:111], v[144:147], v[202:205], v[108:111]
	v_mfma_f32_16x16x32_bf16 v[104:107], v[168:171], v[202:205], v[104:107]
	v_mfma_f32_16x16x32_bf16 v[92:95], v[144:147], v[212:215], v[92:95]
	v_mfma_f32_16x16x32_bf16 v[88:91], v[168:171], v[212:215], v[88:91]
	v_mfma_f32_16x16x32_bf16 v[76:79], v[144:147], v[220:223], v[76:79]
	v_mfma_f32_16x16x32_bf16 v[72:75], v[168:171], v[220:223], v[72:75]
	v_mfma_f32_16x16x32_bf16 v[124:127], v[164:167], v[198:201], v[124:127]
	v_mfma_f32_16x16x32_bf16 v[120:123], v[172:175], v[198:201], v[120:123]
	v_mfma_f32_16x16x32_bf16 v[108:111], v[164:167], v[206:209], v[108:111]
	v_mfma_f32_16x16x32_bf16 v[104:107], v[172:175], v[206:209], v[104:107]
	v_mfma_f32_16x16x32_bf16 v[92:95], v[164:167], v[216:219], v[92:95]
	v_mfma_f32_16x16x32_bf16 v[88:91], v[172:175], v[216:219], v[88:91]
	v_mfma_f32_16x16x32_bf16 v[76:79], v[164:167], v[224:227], v[76:79]
	v_mfma_f32_16x16x32_bf16 v[72:75], v[172:175], v[224:227], v[72:75]
	s_setprio 0
	s_setprio 1
	v_mfma_f32_16x16x32_bf16 v[116:119], v[176:179], v[194:197], v[116:119]
	v_mfma_f32_16x16x32_bf16 v[112:115], v[186:189], v[194:197], v[112:115]
	v_mfma_f32_16x16x32_bf16 v[100:103], v[176:179], v[202:205], v[100:103]
	v_mfma_f32_16x16x32_bf16 v[96:99], v[186:189], v[202:205], v[96:99]
	v_mfma_f32_16x16x32_bf16 v[84:87], v[176:179], v[212:215], v[84:87]
	v_mfma_f32_16x16x32_bf16 v[80:83], v[186:189], v[212:215], v[80:83]
	v_mfma_f32_16x16x32_bf16 v[68:71], v[176:179], v[220:223], v[68:71]
	v_mfma_f32_16x16x32_bf16 v[64:67], v[186:189], v[220:223], v[64:67]
	v_mfma_f32_16x16x32_bf16 v[116:119], v[182:185], v[198:201], v[116:119]
	v_mfma_f32_16x16x32_bf16 v[112:115], v[190:193], v[198:201], v[112:115]
	v_mfma_f32_16x16x32_bf16 v[100:103], v[182:185], v[206:209], v[100:103]
	v_mfma_f32_16x16x32_bf16 v[96:99], v[190:193], v[206:209], v[96:99]
	v_mfma_f32_16x16x32_bf16 v[84:87], v[182:185], v[216:219], v[84:87]
	v_mfma_f32_16x16x32_bf16 v[80:83], v[190:193], v[216:219], v[80:83]
	v_mfma_f32_16x16x32_bf16 v[68:71], v[182:185], v[224:227], v[68:71]
	v_mfma_f32_16x16x32_bf16 v[64:67], v[190:193], v[224:227], v[64:67]
	s_setprio 0
	s_barrier
	s_add_i32 s67, s59, s14
	v_lshl_add_u64 v[228:229], s[46:47], 0, v[130:131]
	s_mov_b32 m0, s67
	ds_read_b128 v[194:197], v163 offset:16384
	ds_read_b128 v[198:201], v163 offset:17408
	ds_read_b128 v[202:205], v163 offset:18432
	ds_read_b128 v[206:209], v163 offset:19456
	ds_read_b128 v[212:215], v163 offset:20480
	ds_read_b128 v[216:219], v163 offset:21504
	ds_read_b128 v[220:223], v163 offset:22528
	ds_read_b128 v[224:227], v163 offset:23552
	global_load_lds_dwordx4 v[228:229], off
	s_add_i32 m0, s67, 0x2000
	s_add_u32 s76, s46, 0x20000
	v_lshl_add_u64 v[230:231], s[46:47], 0, v[134:135]
	s_addc_u32 s77, s47, 0
	s_add_i32 s67, s60, s14
	global_load_lds_dwordx4 v[230:231], off
	v_lshl_add_u64 v[232:233], s[76:77], 0, v[130:131]
	s_mov_b32 m0, s67
	v_lshl_add_u64 v[234:235], s[48:49], 0, v[132:133]
	global_load_lds_dwordx4 v[232:233], off
	v_lshl_add_u64 v[232:233], s[76:77], 0, v[134:135]
	s_add_i32 m0, s67, 0x2000
	s_nop 0
	global_load_lds_dwordx4 v[232:233], off
	v_lshl_add_u64 v[232:233], s[48:49], 0, v[128:129]
	s_mov_b32 m0, s15
	s_nop 0
	global_load_lds_dwordx4 v[232:233], off
	s_mov_b32 m0, s39
	s_nop 0
	global_load_lds_dwordx4 v[234:235], off
	s_waitcnt vmcnt(8)
	s_waitcnt lgkmcnt(0)
	s_barrier
	s_setprio 1
	s_waitcnt lgkmcnt(0)
	v_mfma_f32_16x16x32_bf16 v[60:63], v[144:147], v[194:197], v[60:63]
	v_mfma_f32_16x16x32_bf16 v[56:59], v[168:171], v[194:197], v[56:59]
	v_mfma_f32_16x16x32_bf16 v[44:47], v[144:147], v[202:205], v[44:47]
	v_mfma_f32_16x16x32_bf16 v[40:43], v[168:171], v[202:205], v[40:43]
	v_mfma_f32_16x16x32_bf16 v[28:31], v[144:147], v[212:215], v[28:31]
	v_mfma_f32_16x16x32_bf16 v[24:27], v[168:171], v[212:215], v[24:27]
	v_mfma_f32_16x16x32_bf16 v[12:15], v[144:147], v[220:223], v[12:15]
	v_mfma_f32_16x16x32_bf16 v[8:11], v[168:171], v[220:223], v[8:11]
	v_mfma_f32_16x16x32_bf16 v[60:63], v[164:167], v[198:201], v[60:63]
	v_mfma_f32_16x16x32_bf16 v[56:59], v[172:175], v[198:201], v[56:59]
	v_mfma_f32_16x16x32_bf16 v[44:47], v[164:167], v[206:209], v[44:47]
	v_mfma_f32_16x16x32_bf16 v[40:43], v[172:175], v[206:209], v[40:43]
	v_mfma_f32_16x16x32_bf16 v[28:31], v[164:167], v[216:219], v[28:31]
	v_mfma_f32_16x16x32_bf16 v[24:27], v[172:175], v[216:219], v[24:27]
	v_mfma_f32_16x16x32_bf16 v[12:15], v[164:167], v[224:227], v[12:15]
	v_mfma_f32_16x16x32_bf16 v[8:11], v[172:175], v[224:227], v[8:11]
	s_setprio 0
	s_setprio 1
	v_mfma_f32_16x16x32_bf16 v[52:55], v[176:179], v[194:197], v[52:55]
	v_mfma_f32_16x16x32_bf16 v[48:51], v[186:189], v[194:197], v[48:51]
	v_mfma_f32_16x16x32_bf16 v[36:39], v[176:179], v[202:205], v[36:39]
	v_mfma_f32_16x16x32_bf16 v[32:35], v[186:189], v[202:205], v[32:35]
	v_mfma_f32_16x16x32_bf16 v[20:23], v[176:179], v[212:215], v[20:23]
	v_mfma_f32_16x16x32_bf16 v[16:19], v[186:189], v[212:215], v[16:19]
	v_mfma_f32_16x16x32_bf16 v[4:7], v[176:179], v[220:223], v[4:7]
	v_mfma_f32_16x16x32_bf16 v[0:3], v[186:189], v[220:223], v[0:3]
	v_mfma_f32_16x16x32_bf16 v[52:55], v[182:185], v[198:201], v[52:55]
	v_mfma_f32_16x16x32_bf16 v[48:51], v[190:193], v[198:201], v[48:51]
	v_mfma_f32_16x16x32_bf16 v[36:39], v[182:185], v[206:209], v[36:39]
	v_mfma_f32_16x16x32_bf16 v[32:35], v[190:193], v[206:209], v[32:35]
	v_mfma_f32_16x16x32_bf16 v[20:23], v[182:185], v[216:219], v[20:23]
	v_mfma_f32_16x16x32_bf16 v[16:19], v[190:193], v[216:219], v[16:19]
	v_mfma_f32_16x16x32_bf16 v[4:7], v[182:185], v[224:227], v[4:7]
	v_mfma_f32_16x16x32_bf16 v[0:3], v[190:193], v[224:227], v[0:3]
	s_setprio 0
	s_barrier
	s_add_i32 s67, 0, 0x18000
	s_add_i32 s76, 0, 0x1c000
	v_add_u32_e32 v172, s67, v158
	v_add_u32_e32 v180, s76, v158
	ds_read_b128 v[144:147], v172
	ds_read_b128 v[164:167], v172 offset:1024
	ds_read_b128 v[168:171], v172 offset:2048
	ds_read_b128 v[172:175], v172 offset:3072
	ds_read_b128 v[176:179], v180
	ds_read_b128 v[182:185], v180 offset:1024
	ds_read_b128 v[186:189], v180 offset:2048
	ds_read_b128 v[190:193], v180 offset:3072
	s_add_u32 s48, s48, 0x20000
	s_addc_u32 s49, s49, 0
	s_mov_b32 m0, s53
	v_lshl_add_u64 v[236:237], s[48:49], 0, v[128:129]
	ds_read_b128 v[194:197], v163 offset:32768
	ds_read_b128 v[198:201], v163 offset:33792
	ds_read_b128 v[202:205], v163 offset:34816
	ds_read_b128 v[206:209], v163 offset:35840
	ds_read_b128 v[212:215], v163 offset:36864
	ds_read_b128 v[216:219], v163 offset:37888
	ds_read_b128 v[220:223], v163 offset:38912
	ds_read_b128 v[224:227], v163 offset:39936
	global_load_lds_dwordx4 v[236:237], off
	v_lshl_add_u64 v[236:237], s[48:49], 0, v[132:133]
	s_mov_b32 m0, s54
	s_nop 0
	global_load_lds_dwordx4 v[236:237], off
	s_waitcnt vmcnt(8)
	s_waitcnt lgkmcnt(0)
	s_barrier
	s_setprio 1
	s_waitcnt lgkmcnt(0)
	v_mfma_f32_16x16x32_bf16 v[124:127], v[144:147], v[194:197], v[124:127]
	v_mfma_f32_16x16x32_bf16 v[120:123], v[168:171], v[194:197], v[120:123]
	v_mfma_f32_16x16x32_bf16 v[108:111], v[144:147], v[202:205], v[108:111]
	v_mfma_f32_16x16x32_bf16 v[104:107], v[168:171], v[202:205], v[104:107]
	v_mfma_f32_16x16x32_bf16 v[92:95], v[144:147], v[212:215], v[92:95]
	v_mfma_f32_16x16x32_bf16 v[88:91], v[168:171], v[212:215], v[88:91]
	v_mfma_f32_16x16x32_bf16 v[76:79], v[144:147], v[220:223], v[76:79]
	v_mfma_f32_16x16x32_bf16 v[72:75], v[168:171], v[220:223], v[72:75]
	v_mfma_f32_16x16x32_bf16 v[124:127], v[164:167], v[198:201], v[124:127]
	v_mfma_f32_16x16x32_bf16 v[120:123], v[172:175], v[198:201], v[120:123]
	v_mfma_f32_16x16x32_bf16 v[108:111], v[164:167], v[206:209], v[108:111]
	v_mfma_f32_16x16x32_bf16 v[104:107], v[172:175], v[206:209], v[104:107]
	v_mfma_f32_16x16x32_bf16 v[92:95], v[164:167], v[216:219], v[92:95]
	v_mfma_f32_16x16x32_bf16 v[88:91], v[172:175], v[216:219], v[88:91]
	v_mfma_f32_16x16x32_bf16 v[76:79], v[164:167], v[224:227], v[76:79]
	v_mfma_f32_16x16x32_bf16 v[72:75], v[172:175], v[224:227], v[72:75]
	s_setprio 0
	s_setprio 1
	v_mfma_f32_16x16x32_bf16 v[116:119], v[176:179], v[194:197], v[116:119]
	v_mfma_f32_16x16x32_bf16 v[112:115], v[186:189], v[194:197], v[112:115]
	v_mfma_f32_16x16x32_bf16 v[100:103], v[176:179], v[202:205], v[100:103]
	v_mfma_f32_16x16x32_bf16 v[96:99], v[186:189], v[202:205], v[96:99]
	v_mfma_f32_16x16x32_bf16 v[84:87], v[176:179], v[212:215], v[84:87]
	v_mfma_f32_16x16x32_bf16 v[80:83], v[186:189], v[212:215], v[80:83]
	v_mfma_f32_16x16x32_bf16 v[68:71], v[176:179], v[220:223], v[68:71]
	v_mfma_f32_16x16x32_bf16 v[64:67], v[186:189], v[220:223], v[64:67]
	v_mfma_f32_16x16x32_bf16 v[116:119], v[182:185], v[198:201], v[116:119]
	v_mfma_f32_16x16x32_bf16 v[112:115], v[190:193], v[198:201], v[112:115]
	v_mfma_f32_16x16x32_bf16 v[100:103], v[182:185], v[206:209], v[100:103]
	v_mfma_f32_16x16x32_bf16 v[96:99], v[190:193], v[206:209], v[96:99]
	v_mfma_f32_16x16x32_bf16 v[84:87], v[182:185], v[216:219], v[84:87]
	v_mfma_f32_16x16x32_bf16 v[80:83], v[190:193], v[216:219], v[80:83]
	v_mfma_f32_16x16x32_bf16 v[68:71], v[182:185], v[224:227], v[68:71]
	v_mfma_f32_16x16x32_bf16 v[64:67], v[190:193], v[224:227], v[64:67]
	s_setprio 0
	s_barrier
	s_add_i32 s48, s67, s14
	v_lshl_add_u64 v[228:229], v[228:229], 0, s[18:19]
	s_mov_b32 m0, s48
	ds_read_b128 v[194:197], v163 offset:49152
	ds_read_b128 v[198:201], v163 offset:50176
	ds_read_b128 v[202:205], v163 offset:51200
	ds_read_b128 v[206:209], v163 offset:52224
	ds_read_b128 v[212:215], v163 offset:53248
	ds_read_b128 v[216:219], v163 offset:54272
	ds_read_b128 v[220:223], v163 offset:55296
	ds_read_b128 v[224:227], v163 offset:56320
	global_load_lds_dwordx4 v[228:229], off
	s_add_i32 m0, s48, 0x2000
	s_add_u32 s46, s46, 0x20080
	v_lshl_add_u64 v[228:229], v[230:231], 0, s[18:19]
	s_addc_u32 s47, s47, 0
	s_add_i32 s48, s76, s14
	global_load_lds_dwordx4 v[228:229], off
	v_lshl_add_u64 v[228:229], s[46:47], 0, v[130:131]
	s_mov_b32 m0, s48
	s_nop 0
	global_load_lds_dwordx4 v[228:229], off
	v_lshl_add_u64 v[228:229], s[46:47], 0, v[134:135]
	s_add_i32 m0, s48, 0x2000
	s_nop 0
	global_load_lds_dwordx4 v[228:229], off
	v_lshl_add_u64 v[228:229], v[232:233], 0, s[18:19]
	s_mov_b32 m0, s55
	s_nop 0
	global_load_lds_dwordx4 v[228:229], off
	v_lshl_add_u64 v[228:229], v[234:235], 0, s[18:19]
	s_mov_b32 m0, s57
	s_nop 0
	global_load_lds_dwordx4 v[228:229], off
	s_waitcnt vmcnt(8)
	s_waitcnt lgkmcnt(0)
	s_barrier
	s_setprio 1
	s_waitcnt lgkmcnt(0)
	v_mfma_f32_16x16x32_bf16 v[60:63], v[144:147], v[194:197], v[60:63]
	v_mfma_f32_16x16x32_bf16 v[56:59], v[168:171], v[194:197], v[56:59]
	v_mfma_f32_16x16x32_bf16 v[44:47], v[144:147], v[202:205], v[44:47]
	v_mfma_f32_16x16x32_bf16 v[40:43], v[168:171], v[202:205], v[40:43]
	v_mfma_f32_16x16x32_bf16 v[28:31], v[144:147], v[212:215], v[28:31]
	v_mfma_f32_16x16x32_bf16 v[24:27], v[168:171], v[212:215], v[24:27]
	v_mfma_f32_16x16x32_bf16 v[12:15], v[144:147], v[220:223], v[12:15]
	v_mfma_f32_16x16x32_bf16 v[8:11], v[168:171], v[220:223], v[8:11]
	v_mfma_f32_16x16x32_bf16 v[60:63], v[164:167], v[198:201], v[60:63]
	v_mfma_f32_16x16x32_bf16 v[56:59], v[172:175], v[198:201], v[56:59]
	v_mfma_f32_16x16x32_bf16 v[44:47], v[164:167], v[206:209], v[44:47]
	v_mfma_f32_16x16x32_bf16 v[40:43], v[172:175], v[206:209], v[40:43]
	v_mfma_f32_16x16x32_bf16 v[28:31], v[164:167], v[216:219], v[28:31]
	v_mfma_f32_16x16x32_bf16 v[24:27], v[172:175], v[216:219], v[24:27]
	v_mfma_f32_16x16x32_bf16 v[12:15], v[164:167], v[224:227], v[12:15]
	v_mfma_f32_16x16x32_bf16 v[8:11], v[172:175], v[224:227], v[8:11]
	s_setprio 0
	s_setprio 1
	v_mfma_f32_16x16x32_bf16 v[52:55], v[176:179], v[194:197], v[52:55]
	v_mfma_f32_16x16x32_bf16 v[48:51], v[186:189], v[194:197], v[48:51]
	v_mfma_f32_16x16x32_bf16 v[36:39], v[176:179], v[202:205], v[36:39]
	v_mfma_f32_16x16x32_bf16 v[32:35], v[186:189], v[202:205], v[32:35]
	v_mfma_f32_16x16x32_bf16 v[20:23], v[176:179], v[212:215], v[20:23]
	v_mfma_f32_16x16x32_bf16 v[16:19], v[186:189], v[212:215], v[16:19]
	v_mfma_f32_16x16x32_bf16 v[4:7], v[176:179], v[220:223], v[4:7]
	v_mfma_f32_16x16x32_bf16 v[0:3], v[186:189], v[220:223], v[0:3]
	v_mfma_f32_16x16x32_bf16 v[52:55], v[182:185], v[198:201], v[52:55]
	v_mfma_f32_16x16x32_bf16 v[48:51], v[190:193], v[198:201], v[48:51]
	v_mfma_f32_16x16x32_bf16 v[36:39], v[182:185], v[206:209], v[36:39]
	v_mfma_f32_16x16x32_bf16 v[32:35], v[190:193], v[206:209], v[32:35]
	v_mfma_f32_16x16x32_bf16 v[20:23], v[182:185], v[216:219], v[20:23]
	v_mfma_f32_16x16x32_bf16 v[16:19], v[190:193], v[216:219], v[16:19]
	v_mfma_f32_16x16x32_bf16 v[4:7], v[182:185], v[224:227], v[4:7]
	v_mfma_f32_16x16x32_bf16 v[0:3], v[190:193], v[224:227], v[0:3]
	s_add_i32 s66, s66, 2
	s_add_u32 s44, s44, 0x100
	s_addc_u32 s45, s45, 0
	s_add_u32 s64, s64, 0x100
	s_addc_u32 s65, s65, 0
	s_cmp_gt_u32 s66, 5
	s_setprio 0
	s_barrier
	s_cbranch_scc0 .LBB0_795
	s_and_b64 vcc, exec, s[20:21]
	s_cbranch_vccz .LBB0_798
	s_barrier

.LBB0_892:
	ds_read_b128 v[144:147], v151
	ds_read_b128 v[156:159], v151 offset:1024
	ds_read_b128 v[164:167], v151 offset:2048
	ds_read_b128 v[168:171], v151 offset:3072
	ds_read_b128 v[172:175], v152
	ds_read_b128 v[176:179], v152 offset:1024
	ds_read_b128 v[182:185], v152 offset:2048
	ds_read_b128 v[186:189], v152 offset:3072
	s_add_u32 s46, s44, 0xfffc0080
	s_addc_u32 s47, s45, -1
	s_cmp_eq_u32 s63, 12
	s_cselect_b32 s49, s29, s47
	s_cselect_b32 s48, s39, s46
	s_cselect_b32 s47, s23, s62
	s_cselect_b32 s46, s60, s61
	v_lshl_add_u64 v[160:161], s[44:45], 0, v[136:137]
	s_add_i32 m0, s14, 0xc000
	ds_read_b128 v[190:193], v153
	ds_read_b128 v[194:197], v153 offset:1024
	ds_read_b128 v[198:201], v153 offset:2048
	ds_read_b128 v[202:205], v153 offset:3072
	ds_read_b128 v[206:209], v153 offset:4096
	ds_read_b128 v[212:215], v153 offset:5120
	ds_read_b128 v[216:219], v153 offset:6144
	ds_read_b128 v[220:223], v153 offset:7168
	global_load_lds_dwordx4 v[160:161], off
	v_lshl_add_u64 v[160:161], s[44:45], 0, v[138:139]
	s_add_i32 m0, s14, 0xe000
	s_nop 0
	global_load_lds_dwordx4 v[160:161], off
	s_waitcnt vmcnt(8)
	s_waitcnt lgkmcnt(0)
	s_barrier
	s_setprio 1
	s_waitcnt lgkmcnt(0)
	v_mfma_f32_16x16x32_bf16 v[124:127], v[144:147], v[190:193], v[124:127]
	v_mfma_f32_16x16x32_bf16 v[120:123], v[164:167], v[190:193], v[120:123]
	v_mfma_f32_16x16x32_bf16 v[108:111], v[144:147], v[198:201], v[108:111]
	v_mfma_f32_16x16x32_bf16 v[104:107], v[164:167], v[198:201], v[104:107]
	v_mfma_f32_16x16x32_bf16 v[92:95], v[144:147], v[206:209], v[92:95]
	v_mfma_f32_16x16x32_bf16 v[88:91], v[164:167], v[206:209], v[88:91]
	v_mfma_f32_16x16x32_bf16 v[76:79], v[144:147], v[216:219], v[76:79]
	v_mfma_f32_16x16x32_bf16 v[72:75], v[164:167], v[216:219], v[72:75]
	v_mfma_f32_16x16x32_bf16 v[124:127], v[156:159], v[194:197], v[124:127]
	v_mfma_f32_16x16x32_bf16 v[120:123], v[168:171], v[194:197], v[120:123]
	v_mfma_f32_16x16x32_bf16 v[108:111], v[156:159], v[202:205], v[108:111]
	v_mfma_f32_16x16x32_bf16 v[104:107], v[168:171], v[202:205], v[104:107]
	v_mfma_f32_16x16x32_bf16 v[92:95], v[156:159], v[212:215], v[92:95]
	v_mfma_f32_16x16x32_bf16 v[88:91], v[168:171], v[212:215], v[88:91]
	v_mfma_f32_16x16x32_bf16 v[76:79], v[156:159], v[220:223], v[76:79]
	v_mfma_f32_16x16x32_bf16 v[72:75], v[168:171], v[220:223], v[72:75]
	s_setprio 0
	s_setprio 1
	v_mfma_f32_16x16x32_bf16 v[116:119], v[172:175], v[190:193], v[116:119]
	v_mfma_f32_16x16x32_bf16 v[112:115], v[182:185], v[190:193], v[112:115]
	v_mfma_f32_16x16x32_bf16 v[100:103], v[172:175], v[198:201], v[100:103]
	v_mfma_f32_16x16x32_bf16 v[96:99], v[182:185], v[198:201], v[96:99]
	v_mfma_f32_16x16x32_bf16 v[84:87], v[172:175], v[206:209], v[84:87]
	v_mfma_f32_16x16x32_bf16 v[80:83], v[182:185], v[206:209], v[80:83]
	v_mfma_f32_16x16x32_bf16 v[68:71], v[172:175], v[216:219], v[68:71]
	v_mfma_f32_16x16x32_bf16 v[64:67], v[182:185], v[216:219], v[64:67]
	v_mfma_f32_16x16x32_bf16 v[116:119], v[176:179], v[194:197], v[116:119]
	v_mfma_f32_16x16x32_bf16 v[112:115], v[186:189], v[194:197], v[112:115]
	v_mfma_f32_16x16x32_bf16 v[100:103], v[176:179], v[202:205], v[100:103]
	v_mfma_f32_16x16x32_bf16 v[96:99], v[186:189], v[202:205], v[96:99]
	v_mfma_f32_16x16x32_bf16 v[84:87], v[176:179], v[212:215], v[84:87]
	v_mfma_f32_16x16x32_bf16 v[80:83], v[186:189], v[212:215], v[80:83]
	v_mfma_f32_16x16x32_bf16 v[68:71], v[176:179], v[220:223], v[68:71]
	v_mfma_f32_16x16x32_bf16 v[64:67], v[186:189], v[220:223], v[64:67]
	s_setprio 0
	s_barrier
	s_add_i32 s64, s57, s11
	v_lshl_add_u64 v[160:161], s[46:47], 0, v[130:131]
	s_mov_b32 m0, s64
	ds_read_b128 v[190:193], v153 offset:16384
	ds_read_b128 v[194:197], v153 offset:17408
	ds_read_b128 v[198:201], v153 offset:18432
	ds_read_b128 v[202:205], v153 offset:19456
	ds_read_b128 v[206:209], v153 offset:20480
	ds_read_b128 v[212:215], v153 offset:21504
	ds_read_b128 v[216:219], v153 offset:22528
	ds_read_b128 v[220:223], v153 offset:23552
	global_load_lds_dwordx4 v[160:161], off
	s_add_i32 m0, s64, 0x2000
	s_add_u32 s64, s46, 0x40000
	v_lshl_add_u64 v[224:225], s[46:47], 0, v[134:135]
	s_addc_u32 s65, s47, 0
	s_add_i32 s66, s58, s11
	global_load_lds_dwordx4 v[224:225], off
	v_lshl_add_u64 v[226:227], s[64:65], 0, v[130:131]
	s_mov_b32 m0, s66
	v_lshl_add_u64 v[228:229], s[48:49], 0, v[132:133]
	global_load_lds_dwordx4 v[226:227], off
	v_lshl_add_u64 v[226:227], s[64:65], 0, v[134:135]
	s_add_i32 m0, s66, 0x2000
	s_nop 0
	global_load_lds_dwordx4 v[226:227], off
	v_lshl_add_u64 v[226:227], s[48:49], 0, v[128:129]
	s_mov_b32 m0, s14
	s_nop 0
	global_load_lds_dwordx4 v[226:227], off
	s_mov_b32 m0, s15
	s_nop 0
	global_load_lds_dwordx4 v[228:229], off
	s_waitcnt vmcnt(8)
	s_waitcnt lgkmcnt(0)
	s_barrier
	s_setprio 1
	s_waitcnt lgkmcnt(0)
	v_mfma_f32_16x16x32_bf16 v[60:63], v[144:147], v[190:193], v[60:63]
	v_mfma_f32_16x16x32_bf16 v[56:59], v[164:167], v[190:193], v[56:59]
	v_mfma_f32_16x16x32_bf16 v[44:47], v[144:147], v[198:201], v[44:47]
	v_mfma_f32_16x16x32_bf16 v[40:43], v[164:167], v[198:201], v[40:43]
	v_mfma_f32_16x16x32_bf16 v[28:31], v[144:147], v[206:209], v[28:31]
	v_mfma_f32_16x16x32_bf16 v[24:27], v[164:167], v[206:209], v[24:27]
	v_mfma_f32_16x16x32_bf16 v[12:15], v[144:147], v[216:219], v[12:15]
	v_mfma_f32_16x16x32_bf16 v[8:11], v[164:167], v[216:219], v[8:11]
	v_mfma_f32_16x16x32_bf16 v[60:63], v[156:159], v[194:197], v[60:63]
	v_mfma_f32_16x16x32_bf16 v[56:59], v[168:171], v[194:197], v[56:59]
	v_mfma_f32_16x16x32_bf16 v[44:47], v[156:159], v[202:205], v[44:47]
	v_mfma_f32_16x16x32_bf16 v[40:43], v[168:171], v[202:205], v[40:43]
	v_mfma_f32_16x16x32_bf16 v[28:31], v[156:159], v[212:215], v[28:31]
	v_mfma_f32_16x16x32_bf16 v[24:27], v[168:171], v[212:215], v[24:27]
	v_mfma_f32_16x16x32_bf16 v[12:15], v[156:159], v[220:223], v[12:15]
	v_mfma_f32_16x16x32_bf16 v[8:11], v[168:171], v[220:223], v[8:11]
	s_setprio 0
	s_setprio 1
	v_mfma_f32_16x16x32_bf16 v[52:55], v[172:175], v[190:193], v[52:55]
	v_mfma_f32_16x16x32_bf16 v[48:51], v[182:185], v[190:193], v[48:51]
	v_mfma_f32_16x16x32_bf16 v[36:39], v[172:175], v[198:201], v[36:39]
	v_mfma_f32_16x16x32_bf16 v[32:35], v[182:185], v[198:201], v[32:35]
	v_mfma_f32_16x16x32_bf16 v[20:23], v[172:175], v[206:209], v[20:23]
	v_mfma_f32_16x16x32_bf16 v[16:19], v[182:185], v[206:209], v[16:19]
	v_mfma_f32_16x16x32_bf16 v[4:7], v[172:175], v[216:219], v[4:7]
	v_mfma_f32_16x16x32_bf16 v[0:3], v[182:185], v[216:219], v[0:3]
	v_mfma_f32_16x16x32_bf16 v[52:55], v[176:179], v[194:197], v[52:55]
	v_mfma_f32_16x16x32_bf16 v[48:51], v[186:189], v[194:197], v[48:51]
	v_mfma_f32_16x16x32_bf16 v[36:39], v[176:179], v[202:205], v[36:39]
	v_mfma_f32_16x16x32_bf16 v[32:35], v[186:189], v[202:205], v[32:35]
	v_mfma_f32_16x16x32_bf16 v[20:23], v[176:179], v[212:215], v[20:23]
	v_mfma_f32_16x16x32_bf16 v[16:19], v[186:189], v[212:215], v[16:19]
	v_mfma_f32_16x16x32_bf16 v[4:7], v[176:179], v[220:223], v[4:7]
	v_mfma_f32_16x16x32_bf16 v[0:3], v[186:189], v[220:223], v[0:3]
	s_setprio 0
	s_barrier
	s_add_i32 s64, 0, 0x18000
	v_add_u32_e32 v155, s64, v149
	s_add_i32 s65, 0, 0x1c000
	ds_read_b128 v[144:147], v155
	ds_read_b128 v[156:159], v155 offset:1024
	ds_read_b128 v[164:167], v155 offset:2048
	ds_read_b128 v[168:171], v155 offset:3072
	v_add_u32_e32 v155, s65, v149
	ds_read_b128 v[172:175], v155
	ds_read_b128 v[176:179], v155 offset:1024
	ds_read_b128 v[182:185], v155 offset:2048
	ds_read_b128 v[186:189], v155 offset:3072
	s_add_u32 s48, s48, 0x40000
	s_addc_u32 s49, s49, 0
	s_mov_b32 m0, s50
	v_lshl_add_u64 v[230:231], s[48:49], 0, v[128:129]
	ds_read_b128 v[190:193], v153 offset:32768
	ds_read_b128 v[194:197], v153 offset:33792
	ds_read_b128 v[198:201], v153 offset:34816
	ds_read_b128 v[202:205], v153 offset:35840
	ds_read_b128 v[206:209], v153 offset:36864
	ds_read_b128 v[212:215], v153 offset:37888
	ds_read_b128 v[216:219], v153 offset:38912
	ds_read_b128 v[220:223], v153 offset:39936
	global_load_lds_dwordx4 v[230:231], off
	v_lshl_add_u64 v[230:231], s[48:49], 0, v[132:133]
	s_mov_b32 m0, s51
	s_nop 0
	global_load_lds_dwordx4 v[230:231], off
	s_waitcnt vmcnt(8)
	s_waitcnt lgkmcnt(0)
	s_barrier
	s_setprio 1
	s_waitcnt lgkmcnt(0)
	v_mfma_f32_16x16x32_bf16 v[124:127], v[144:147], v[190:193], v[124:127]
	v_mfma_f32_16x16x32_bf16 v[120:123], v[164:167], v[190:193], v[120:123]
	v_mfma_f32_16x16x32_bf16 v[108:111], v[144:147], v[198:201], v[108:111]
	v_mfma_f32_16x16x32_bf16 v[104:107], v[164:167], v[198:201], v[104:107]
	v_mfma_f32_16x16x32_bf16 v[92:95], v[144:147], v[206:209], v[92:95]
	v_mfma_f32_16x16x32_bf16 v[88:91], v[164:167], v[206:209], v[88:91]
	v_mfma_f32_16x16x32_bf16 v[76:79], v[144:147], v[216:219], v[76:79]
	v_mfma_f32_16x16x32_bf16 v[72:75], v[164:167], v[216:219], v[72:75]
	v_mfma_f32_16x16x32_bf16 v[124:127], v[156:159], v[194:197], v[124:127]
	v_mfma_f32_16x16x32_bf16 v[120:123], v[168:171], v[194:197], v[120:123]
	v_mfma_f32_16x16x32_bf16 v[108:111], v[156:159], v[202:205], v[108:111]
	v_mfma_f32_16x16x32_bf16 v[104:107], v[168:171], v[202:205], v[104:107]
	v_mfma_f32_16x16x32_bf16 v[92:95], v[156:159], v[212:215], v[92:95]
	v_mfma_f32_16x16x32_bf16 v[88:91], v[168:171], v[212:215], v[88:91]
	v_mfma_f32_16x16x32_bf16 v[76:79], v[156:159], v[220:223], v[76:79]
	v_mfma_f32_16x16x32_bf16 v[72:75], v[168:171], v[220:223], v[72:75]
	s_setprio 0
	s_setprio 1
	v_mfma_f32_16x16x32_bf16 v[116:119], v[172:175], v[190:193], v[116:119]
	v_mfma_f32_16x16x32_bf16 v[112:115], v[182:185], v[190:193], v[112:115]
	v_mfma_f32_16x16x32_bf16 v[100:103], v[172:175], v[198:201], v[100:103]
	v_mfma_f32_16x16x32_bf16 v[96:99], v[182:185], v[198:201], v[96:99]
	v_mfma_f32_16x16x32_bf16 v[84:87], v[172:175], v[206:209], v[84:87]
	v_mfma_f32_16x16x32_bf16 v[80:83], v[182:185], v[206:209], v[80:83]
	v_mfma_f32_16x16x32_bf16 v[68:71], v[172:175], v[216:219], v[68:71]
	v_mfma_f32_16x16x32_bf16 v[64:67], v[182:185], v[216:219], v[64:67]
	v_mfma_f32_16x16x32_bf16 v[116:119], v[176:179], v[194:197], v[116:119]
	v_mfma_f32_16x16x32_bf16 v[112:115], v[186:189], v[194:197], v[112:115]
	v_mfma_f32_16x16x32_bf16 v[100:103], v[176:179], v[202:205], v[100:103]
	v_mfma_f32_16x16x32_bf16 v[96:99], v[186:189], v[202:205], v[96:99]
	v_mfma_f32_16x16x32_bf16 v[84:87], v[176:179], v[212:215], v[84:87]
	v_mfma_f32_16x16x32_bf16 v[80:83], v[186:189], v[212:215], v[80:83]
	v_mfma_f32_16x16x32_bf16 v[68:71], v[176:179], v[220:223], v[68:71]
	v_mfma_f32_16x16x32_bf16 v[64:67], v[186:189], v[220:223], v[64:67]
	s_setprio 0
	s_barrier
	s_add_i32 s48, s64, s11
	v_lshl_add_u64 v[160:161], v[160:161], 0, s[18:19]
	s_mov_b32 m0, s48
	ds_read_b128 v[190:193], v153 offset:49152
	ds_read_b128 v[194:197], v153 offset:50176
	ds_read_b128 v[198:201], v153 offset:51200
	ds_read_b128 v[202:205], v153 offset:52224
	ds_read_b128 v[206:209], v153 offset:53248
	ds_read_b128 v[212:215], v153 offset:54272
	ds_read_b128 v[216:219], v153 offset:55296
	ds_read_b128 v[220:223], v153 offset:56320
	global_load_lds_dwordx4 v[160:161], off
	s_add_i32 m0, s48, 0x2000
	s_add_u32 s46, s46, 0x40080
	v_lshl_add_u64 v[160:161], v[224:225], 0, s[18:19]
	s_addc_u32 s47, s47, 0
	s_add_i32 s48, s65, s11
	global_load_lds_dwordx4 v[160:161], off
	v_lshl_add_u64 v[160:161], s[46:47], 0, v[130:131]
	s_mov_b32 m0, s48
	s_nop 0
	global_load_lds_dwordx4 v[160:161], off
	v_lshl_add_u64 v[160:161], s[46:47], 0, v[134:135]
	s_add_i32 m0, s48, 0x2000
	s_nop 0
	global_load_lds_dwordx4 v[160:161], off
	v_lshl_add_u64 v[160:161], v[226:227], 0, s[18:19]
	s_mov_b32 m0, s55
	s_nop 0
	global_load_lds_dwordx4 v[160:161], off
	v_lshl_add_u64 v[160:161], v[228:229], 0, s[18:19]
	s_mov_b32 m0, s56
	s_nop 0
	global_load_lds_dwordx4 v[160:161], off
	s_waitcnt vmcnt(8)
	s_waitcnt lgkmcnt(0)
	s_barrier
	s_setprio 1
	s_waitcnt lgkmcnt(0)
	v_mfma_f32_16x16x32_bf16 v[60:63], v[144:147], v[190:193], v[60:63]
	v_mfma_f32_16x16x32_bf16 v[56:59], v[164:167], v[190:193], v[56:59]
	v_mfma_f32_16x16x32_bf16 v[44:47], v[144:147], v[198:201], v[44:47]
	v_mfma_f32_16x16x32_bf16 v[40:43], v[164:167], v[198:201], v[40:43]
	v_mfma_f32_16x16x32_bf16 v[28:31], v[144:147], v[206:209], v[28:31]
	v_mfma_f32_16x16x32_bf16 v[24:27], v[164:167], v[206:209], v[24:27]
	v_mfma_f32_16x16x32_bf16 v[12:15], v[144:147], v[216:219], v[12:15]
	v_mfma_f32_16x16x32_bf16 v[8:11], v[164:167], v[216:219], v[8:11]
	v_mfma_f32_16x16x32_bf16 v[60:63], v[156:159], v[194:197], v[60:63]
	v_mfma_f32_16x16x32_bf16 v[56:59], v[168:171], v[194:197], v[56:59]
	v_mfma_f32_16x16x32_bf16 v[44:47], v[156:159], v[202:205], v[44:47]
	v_mfma_f32_16x16x32_bf16 v[40:43], v[168:171], v[202:205], v[40:43]
	v_mfma_f32_16x16x32_bf16 v[28:31], v[156:159], v[212:215], v[28:31]
	v_mfma_f32_16x16x32_bf16 v[24:27], v[168:171], v[212:215], v[24:27]
	v_mfma_f32_16x16x32_bf16 v[12:15], v[156:159], v[220:223], v[12:15]
	v_mfma_f32_16x16x32_bf16 v[8:11], v[168:171], v[220:223], v[8:11]
	s_setprio 0
	s_setprio 1
	v_mfma_f32_16x16x32_bf16 v[52:55], v[172:175], v[190:193], v[52:55]
	v_mfma_f32_16x16x32_bf16 v[48:51], v[182:185], v[190:193], v[48:51]
	v_mfma_f32_16x16x32_bf16 v[36:39], v[172:175], v[198:201], v[36:39]
	v_mfma_f32_16x16x32_bf16 v[32:35], v[182:185], v[198:201], v[32:35]
	v_mfma_f32_16x16x32_bf16 v[20:23], v[172:175], v[206:209], v[20:23]
	v_mfma_f32_16x16x32_bf16 v[16:19], v[182:185], v[206:209], v[16:19]
	v_mfma_f32_16x16x32_bf16 v[4:7], v[172:175], v[216:219], v[4:7]
	v_mfma_f32_16x16x32_bf16 v[0:3], v[182:185], v[216:219], v[0:3]
	v_mfma_f32_16x16x32_bf16 v[52:55], v[176:179], v[194:197], v[52:55]
	v_mfma_f32_16x16x32_bf16 v[48:51], v[186:189], v[194:197], v[48:51]
	v_mfma_f32_16x16x32_bf16 v[36:39], v[176:179], v[202:205], v[36:39]
	v_mfma_f32_16x16x32_bf16 v[32:35], v[186:189], v[202:205], v[32:35]
	v_mfma_f32_16x16x32_bf16 v[20:23], v[176:179], v[212:215], v[20:23]
	v_mfma_f32_16x16x32_bf16 v[16:19], v[186:189], v[212:215], v[16:19]
	v_mfma_f32_16x16x32_bf16 v[4:7], v[176:179], v[220:223], v[4:7]
	v_mfma_f32_16x16x32_bf16 v[0:3], v[186:189], v[220:223], v[0:3]
	s_add_i32 s63, s63, 2
	s_add_u32 s44, s44, 0x100
	s_addc_u32 s45, s45, 0
	s_add_u32 s61, s61, 0x100
	s_addc_u32 s62, s62, 0
	s_cmp_gt_u32 s63, 13
	s_setprio 0
	s_barrier
	s_cbranch_scc0 .LBB0_892
	s_and_b64 vcc, exec, s[20:21]
	s_cbranch_vccz .LBB0_895
	s_barrier

.LBB0_981:
	ds_read_b128 v[128:131], v216
	ds_read_b128 v[132:135], v216 offset:1024
	ds_read_b128 v[136:139], v216 offset:2048
	ds_read_b128 v[140:143], v216 offset:3072
	ds_read_b128 v[144:147], v217
	ds_read_b128 v[148:151], v217 offset:1024
	ds_read_b128 v[152:155], v217 offset:2048
	ds_read_b128 v[156:159], v217 offset:3072
	s_add_u32 s60, s6, 0xfffc0080
	s_addc_u32 s61, s7, -1
	s_cmp_eq_u32 s92, 12
	s_cselect_b32 s63, s9, s61
	s_cselect_b32 s62, s14, s60
	s_cselect_b32 s61, s15, s55
	s_cselect_b32 s60, s29, s53
	v_lshl_add_u64 v[160:161], s[6:7], 0, v[196:197]
	s_add_i32 m0, s64, 0xc000
	ds_read_b128 v[204:207], v213
	ds_read_b128 v[220:223], v213 offset:1024
	ds_read_b128 v[224:227], v213 offset:2048
	ds_read_b128 v[228:231], v213 offset:3072
	ds_read_b128 v[232:235], v213 offset:4096
	ds_read_b128 v[236:239], v213 offset:5120
	ds_read_b128 v[240:243], v213 offset:6144
	ds_read_b128 v[244:247], v213 offset:7168
	global_load_lds_dwordx4 v[160:161], off
	v_lshl_add_u64 v[160:161], s[6:7], 0, v[198:199]
	s_add_i32 m0, s64, 0xe000
	s_nop 0
	global_load_lds_dwordx4 v[160:161], off
	s_waitcnt vmcnt(8)
	s_waitcnt lgkmcnt(0)
	s_barrier
	s_setprio 1
	s_waitcnt lgkmcnt(0)
	v_mfma_f32_16x16x32_bf16 v[116:119], v[128:131], v[204:207], v[116:119]
	v_mfma_f32_16x16x32_bf16 v[24:27], v[136:139], v[204:207], v[24:27]
	v_mfma_f32_16x16x32_bf16 v[124:127], v[128:131], v[224:227], v[124:127]
	v_mfma_f32_16x16x32_bf16 v[32:35], v[136:139], v[224:227], v[32:35]
	v_mfma_f32_16x16x32_bf16 v[120:123], v[128:131], v[232:235], v[120:123]
	v_mfma_f32_16x16x32_bf16 v[44:47], v[136:139], v[232:235], v[44:47]
	v_mfma_f32_16x16x32_bf16 v[112:115], v[128:131], v[240:243], v[112:115]
	v_mfma_f32_16x16x32_bf16 v[52:55], v[136:139], v[240:243], v[52:55]
	v_mfma_f32_16x16x32_bf16 v[116:119], v[132:135], v[220:223], v[116:119]
	v_mfma_f32_16x16x32_bf16 v[24:27], v[140:143], v[220:223], v[24:27]
	v_mfma_f32_16x16x32_bf16 v[124:127], v[132:135], v[228:231], v[124:127]
	v_mfma_f32_16x16x32_bf16 v[32:35], v[140:143], v[228:231], v[32:35]
	v_mfma_f32_16x16x32_bf16 v[120:123], v[132:135], v[236:239], v[120:123]
	v_mfma_f32_16x16x32_bf16 v[44:47], v[140:143], v[236:239], v[44:47]
	v_mfma_f32_16x16x32_bf16 v[112:115], v[132:135], v[244:247], v[112:115]
	v_mfma_f32_16x16x32_bf16 v[52:55], v[140:143], v[244:247], v[52:55]
	s_setprio 0
	s_setprio 1
	v_mfma_f32_16x16x32_bf16 v[72:75], v[144:147], v[204:207], v[72:75]
	v_mfma_f32_16x16x32_bf16 v[0:3], v[152:155], v[204:207], v[0:3]
	v_mfma_f32_16x16x32_bf16 v[88:91], v[144:147], v[224:227], v[88:91]
	v_mfma_f32_16x16x32_bf16 v[4:7], v[152:155], v[224:227], v[4:7]
	v_mfma_f32_16x16x32_bf16 v[104:107], v[144:147], v[232:235], v[104:107]
	v_mfma_f32_16x16x32_bf16 v[12:15], v[152:155], v[232:235], v[12:15]
	v_mfma_f32_16x16x32_bf16 v[108:111], v[144:147], v[240:243], v[108:111]
	v_mfma_f32_16x16x32_bf16 v[20:23], v[152:155], v[240:243], v[20:23]
	v_mfma_f32_16x16x32_bf16 v[72:75], v[148:151], v[220:223], v[72:75]
	v_mfma_f32_16x16x32_bf16 v[0:3], v[156:159], v[220:223], v[0:3]
	v_mfma_f32_16x16x32_bf16 v[88:91], v[148:151], v[228:231], v[88:91]
	v_mfma_f32_16x16x32_bf16 v[4:7], v[156:159], v[228:231], v[4:7]
	v_mfma_f32_16x16x32_bf16 v[104:107], v[148:151], v[236:239], v[104:107]
	v_mfma_f32_16x16x32_bf16 v[12:15], v[156:159], v[236:239], v[12:15]
	v_mfma_f32_16x16x32_bf16 v[108:111], v[148:151], v[244:247], v[108:111]
	v_mfma_f32_16x16x32_bf16 v[20:23], v[156:159], v[244:247], v[20:23]
	s_setprio 0
	s_barrier
	s_add_i32 s93, s82, s11
	v_lshl_add_u64 v[160:161], s[60:61], 0, v[166:167]
	s_mov_b32 m0, s93
	ds_read_b128 v[204:207], v213 offset:16384
	ds_read_b128 v[220:223], v213 offset:17408
	ds_read_b128 v[224:227], v213 offset:18432
	ds_read_b128 v[228:231], v213 offset:19456
	ds_read_b128 v[232:235], v213 offset:20480
	ds_read_b128 v[236:239], v213 offset:21504
	ds_read_b128 v[240:243], v213 offset:22528
	ds_read_b128 v[244:247], v213 offset:23552
	global_load_lds_dwordx4 v[160:161], off
	s_add_i32 m0, s93, 0x2000
	s_add_u32 s94, s60, 0x40000
	v_lshl_add_u64 v[208:209], s[60:61], 0, v[170:171]
	s_addc_u32 s95, s61, 0
	s_add_i32 s93, s83, s11
	global_load_lds_dwordx4 v[208:209], off
	v_lshl_add_u64 v[248:249], s[94:95], 0, v[166:167]
	s_mov_b32 m0, s93
	v_lshl_add_u64 v[250:251], s[62:63], 0, v[168:169]
	global_load_lds_dwordx4 v[248:249], off
	v_lshl_add_u64 v[248:249], s[94:95], 0, v[170:171]
	s_add_i32 m0, s93, 0x2000
	s_nop 0
	global_load_lds_dwordx4 v[248:249], off
	v_lshl_add_u64 v[248:249], s[62:63], 0, v[164:165]
	s_mov_b32 m0, s64
	s_nop 0
	global_load_lds_dwordx4 v[248:249], off
	s_mov_b32 m0, s65
	s_nop 0
	global_load_lds_dwordx4 v[250:251], off
	s_waitcnt vmcnt(8)
	s_waitcnt lgkmcnt(0)
	s_barrier
	s_setprio 1
	s_waitcnt lgkmcnt(0)
	v_mfma_f32_16x16x32_bf16 v[100:103], v[128:131], v[204:207], v[100:103]
	v_mfma_f32_16x16x32_bf16 v[40:43], v[136:139], v[204:207], v[40:43]
	v_mfma_f32_16x16x32_bf16 v[92:95], v[128:131], v[224:227], v[92:95]
	v_mfma_f32_16x16x32_bf16 v[48:51], v[136:139], v[224:227], v[48:51]
	v_mfma_f32_16x16x32_bf16 v[80:83], v[128:131], v[232:235], v[80:83]
	v_mfma_f32_16x16x32_bf16 v[56:59], v[136:139], v[232:235], v[56:59]
	v_mfma_f32_16x16x32_bf16 v[68:71], v[128:131], v[240:243], v[68:71]
	v_mfma_f32_16x16x32_bf16 v[60:63], v[136:139], v[240:243], v[60:63]
	v_mfma_f32_16x16x32_bf16 v[100:103], v[132:135], v[220:223], v[100:103]
	v_mfma_f32_16x16x32_bf16 v[40:43], v[140:143], v[220:223], v[40:43]
	v_mfma_f32_16x16x32_bf16 v[92:95], v[132:135], v[228:231], v[92:95]
	v_mfma_f32_16x16x32_bf16 v[48:51], v[140:143], v[228:231], v[48:51]
	v_mfma_f32_16x16x32_bf16 v[80:83], v[132:135], v[236:239], v[80:83]
	v_mfma_f32_16x16x32_bf16 v[56:59], v[140:143], v[236:239], v[56:59]
	v_mfma_f32_16x16x32_bf16 v[68:71], v[132:135], v[244:247], v[68:71]
	v_mfma_f32_16x16x32_bf16 v[60:63], v[140:143], v[244:247], v[60:63]
	s_setprio 0
	s_setprio 1
	v_mfma_f32_16x16x32_bf16 v[96:99], v[144:147], v[204:207], v[96:99]
	v_mfma_f32_16x16x32_bf16 v[8:11], v[152:155], v[204:207], v[8:11]
	v_mfma_f32_16x16x32_bf16 v[84:87], v[144:147], v[224:227], v[84:87]
	v_mfma_f32_16x16x32_bf16 v[16:19], v[152:155], v[224:227], v[16:19]
	v_mfma_f32_16x16x32_bf16 v[76:79], v[144:147], v[232:235], v[76:79]
	v_mfma_f32_16x16x32_bf16 v[28:31], v[152:155], v[232:235], v[28:31]
	v_mfma_f32_16x16x32_bf16 v[64:67], v[144:147], v[240:243], v[64:67]
	v_mfma_f32_16x16x32_bf16 v[36:39], v[152:155], v[240:243], v[36:39]
	v_mfma_f32_16x16x32_bf16 v[96:99], v[148:151], v[220:223], v[96:99]
	v_mfma_f32_16x16x32_bf16 v[8:11], v[156:159], v[220:223], v[8:11]
	v_mfma_f32_16x16x32_bf16 v[84:87], v[148:151], v[228:231], v[84:87]
	v_mfma_f32_16x16x32_bf16 v[16:19], v[156:159], v[228:231], v[16:19]
	v_mfma_f32_16x16x32_bf16 v[76:79], v[148:151], v[236:239], v[76:79]
	v_mfma_f32_16x16x32_bf16 v[28:31], v[156:159], v[236:239], v[28:31]
	v_mfma_f32_16x16x32_bf16 v[64:67], v[148:151], v[244:247], v[64:67]
	v_mfma_f32_16x16x32_bf16 v[36:39], v[156:159], v[244:247], v[36:39]
	s_setprio 0
	s_barrier
	s_add_i32 s93, 0, 0x18000
	s_add_i32 s94, 0, 0x1c000
	v_add_u32_e32 v140, s93, v163
	v_add_u32_e32 v156, s94, v163
	ds_read_b128 v[128:131], v140
	ds_read_b128 v[132:135], v140 offset:1024
	ds_read_b128 v[136:139], v140 offset:2048
	ds_read_b128 v[140:143], v140 offset:3072
	ds_read_b128 v[144:147], v156
	ds_read_b128 v[148:151], v156 offset:1024
	ds_read_b128 v[152:155], v156 offset:2048
	ds_read_b128 v[156:159], v156 offset:3072
	s_add_u32 s62, s62, 0x40000
	s_addc_u32 s63, s63, 0
	s_mov_b32 m0, s66
	v_lshl_add_u64 v[252:253], s[62:63], 0, v[164:165]
	ds_read_b128 v[204:207], v213 offset:32768
	ds_read_b128 v[220:223], v213 offset:33792
	ds_read_b128 v[224:227], v213 offset:34816
	ds_read_b128 v[228:231], v213 offset:35840
	ds_read_b128 v[232:235], v213 offset:36864
	ds_read_b128 v[236:239], v213 offset:37888
	ds_read_b128 v[240:243], v213 offset:38912
	ds_read_b128 v[244:247], v213 offset:39936
	global_load_lds_dwordx4 v[252:253], off
	v_lshl_add_u64 v[252:253], s[62:63], 0, v[168:169]
	s_mov_b32 m0, s67
	s_nop 0
	global_load_lds_dwordx4 v[252:253], off
	s_waitcnt vmcnt(8)
	s_waitcnt lgkmcnt(0)
	s_barrier
	s_setprio 1
	s_waitcnt lgkmcnt(0)
	v_mfma_f32_16x16x32_bf16 v[116:119], v[128:131], v[204:207], v[116:119]
	v_mfma_f32_16x16x32_bf16 v[24:27], v[136:139], v[204:207], v[24:27]
	v_mfma_f32_16x16x32_bf16 v[124:127], v[128:131], v[224:227], v[124:127]
	v_mfma_f32_16x16x32_bf16 v[32:35], v[136:139], v[224:227], v[32:35]
	v_mfma_f32_16x16x32_bf16 v[120:123], v[128:131], v[232:235], v[120:123]
	v_mfma_f32_16x16x32_bf16 v[44:47], v[136:139], v[232:235], v[44:47]
	v_mfma_f32_16x16x32_bf16 v[112:115], v[128:131], v[240:243], v[112:115]
	v_mfma_f32_16x16x32_bf16 v[52:55], v[136:139], v[240:243], v[52:55]
	v_mfma_f32_16x16x32_bf16 v[116:119], v[132:135], v[220:223], v[116:119]
	v_mfma_f32_16x16x32_bf16 v[24:27], v[140:143], v[220:223], v[24:27]
	v_mfma_f32_16x16x32_bf16 v[124:127], v[132:135], v[228:231], v[124:127]
	v_mfma_f32_16x16x32_bf16 v[32:35], v[140:143], v[228:231], v[32:35]
	v_mfma_f32_16x16x32_bf16 v[120:123], v[132:135], v[236:239], v[120:123]
	v_mfma_f32_16x16x32_bf16 v[44:47], v[140:143], v[236:239], v[44:47]
	v_mfma_f32_16x16x32_bf16 v[112:115], v[132:135], v[244:247], v[112:115]
	v_mfma_f32_16x16x32_bf16 v[52:55], v[140:143], v[244:247], v[52:55]
	s_setprio 0
	s_setprio 1
	v_mfma_f32_16x16x32_bf16 v[72:75], v[144:147], v[204:207], v[72:75]
	v_mfma_f32_16x16x32_bf16 v[0:3], v[152:155], v[204:207], v[0:3]
	v_mfma_f32_16x16x32_bf16 v[88:91], v[144:147], v[224:227], v[88:91]
	v_mfma_f32_16x16x32_bf16 v[4:7], v[152:155], v[224:227], v[4:7]
	v_mfma_f32_16x16x32_bf16 v[104:107], v[144:147], v[232:235], v[104:107]
	v_mfma_f32_16x16x32_bf16 v[12:15], v[152:155], v[232:235], v[12:15]
	v_mfma_f32_16x16x32_bf16 v[108:111], v[144:147], v[240:243], v[108:111]
	v_mfma_f32_16x16x32_bf16 v[20:23], v[152:155], v[240:243], v[20:23]
	v_mfma_f32_16x16x32_bf16 v[72:75], v[148:151], v[220:223], v[72:75]
	v_mfma_f32_16x16x32_bf16 v[0:3], v[156:159], v[220:223], v[0:3]
	v_mfma_f32_16x16x32_bf16 v[88:91], v[148:151], v[228:231], v[88:91]
	v_mfma_f32_16x16x32_bf16 v[4:7], v[156:159], v[228:231], v[4:7]
	v_mfma_f32_16x16x32_bf16 v[104:107], v[148:151], v[236:239], v[104:107]
	v_mfma_f32_16x16x32_bf16 v[12:15], v[156:159], v[236:239], v[12:15]
	v_mfma_f32_16x16x32_bf16 v[108:111], v[148:151], v[244:247], v[108:111]
	v_mfma_f32_16x16x32_bf16 v[20:23], v[156:159], v[244:247], v[20:23]
	s_setprio 0
	s_barrier
	s_add_i32 s62, s93, s11
	v_lshl_add_u64 v[160:161], v[160:161], 0, s[44:45]
	s_mov_b32 m0, s62
	ds_read_b128 v[204:207], v213 offset:49152
	ds_read_b128 v[220:223], v213 offset:50176
	ds_read_b128 v[224:227], v213 offset:51200
	ds_read_b128 v[228:231], v213 offset:52224
	ds_read_b128 v[232:235], v213 offset:53248
	ds_read_b128 v[236:239], v213 offset:54272
	ds_read_b128 v[240:243], v213 offset:55296
	ds_read_b128 v[244:247], v213 offset:56320
	global_load_lds_dwordx4 v[160:161], off
	s_add_i32 m0, s62, 0x2000
	s_add_u32 s60, s60, 0x40080
	v_lshl_add_u64 v[160:161], v[208:209], 0, s[44:45]
	s_addc_u32 s61, s61, 0
	s_add_i32 s62, s94, s11
	global_load_lds_dwordx4 v[160:161], off
	v_lshl_add_u64 v[160:161], s[60:61], 0, v[166:167]
	s_mov_b32 m0, s62
	s_nop 0
	global_load_lds_dwordx4 v[160:161], off
	v_lshl_add_u64 v[160:161], s[60:61], 0, v[170:171]
	s_add_i32 m0, s62, 0x2000
	s_nop 0
	global_load_lds_dwordx4 v[160:161], off
	v_lshl_add_u64 v[160:161], v[248:249], 0, s[44:45]
	s_mov_b32 m0, s80
	s_nop 0
	global_load_lds_dwordx4 v[160:161], off
	v_lshl_add_u64 v[160:161], v[250:251], 0, s[44:45]
	s_mov_b32 m0, s81
	s_nop 0
	global_load_lds_dwordx4 v[160:161], off
	s_waitcnt vmcnt(8)
	s_waitcnt lgkmcnt(0)
	s_barrier
	s_setprio 1
	s_waitcnt lgkmcnt(0)
	v_mfma_f32_16x16x32_bf16 v[100:103], v[128:131], v[204:207], v[100:103]
	v_mfma_f32_16x16x32_bf16 v[40:43], v[136:139], v[204:207], v[40:43]
	v_mfma_f32_16x16x32_bf16 v[92:95], v[128:131], v[224:227], v[92:95]
	v_mfma_f32_16x16x32_bf16 v[48:51], v[136:139], v[224:227], v[48:51]
	v_mfma_f32_16x16x32_bf16 v[80:83], v[128:131], v[232:235], v[80:83]
	v_mfma_f32_16x16x32_bf16 v[56:59], v[136:139], v[232:235], v[56:59]
	v_mfma_f32_16x16x32_bf16 v[68:71], v[128:131], v[240:243], v[68:71]
	v_mfma_f32_16x16x32_bf16 v[60:63], v[136:139], v[240:243], v[60:63]
	v_mfma_f32_16x16x32_bf16 v[100:103], v[132:135], v[220:223], v[100:103]
	v_mfma_f32_16x16x32_bf16 v[40:43], v[140:143], v[220:223], v[40:43]
	v_mfma_f32_16x16x32_bf16 v[92:95], v[132:135], v[228:231], v[92:95]
	v_mfma_f32_16x16x32_bf16 v[48:51], v[140:143], v[228:231], v[48:51]
	v_mfma_f32_16x16x32_bf16 v[80:83], v[132:135], v[236:239], v[80:83]
	v_mfma_f32_16x16x32_bf16 v[56:59], v[140:143], v[236:239], v[56:59]
	v_mfma_f32_16x16x32_bf16 v[68:71], v[132:135], v[244:247], v[68:71]
	v_mfma_f32_16x16x32_bf16 v[60:63], v[140:143], v[244:247], v[60:63]
	s_setprio 0
	s_setprio 1
	v_mfma_f32_16x16x32_bf16 v[96:99], v[144:147], v[204:207], v[96:99]
	v_mfma_f32_16x16x32_bf16 v[8:11], v[152:155], v[204:207], v[8:11]
	v_mfma_f32_16x16x32_bf16 v[84:87], v[144:147], v[224:227], v[84:87]
	v_mfma_f32_16x16x32_bf16 v[16:19], v[152:155], v[224:227], v[16:19]
	v_mfma_f32_16x16x32_bf16 v[76:79], v[144:147], v[232:235], v[76:79]
	v_mfma_f32_16x16x32_bf16 v[28:31], v[152:155], v[232:235], v[28:31]
	v_mfma_f32_16x16x32_bf16 v[64:67], v[144:147], v[240:243], v[64:67]
	v_mfma_f32_16x16x32_bf16 v[36:39], v[152:155], v[240:243], v[36:39]
	v_mfma_f32_16x16x32_bf16 v[96:99], v[148:151], v[220:223], v[96:99]
	v_mfma_f32_16x16x32_bf16 v[8:11], v[156:159], v[220:223], v[8:11]
	v_mfma_f32_16x16x32_bf16 v[84:87], v[148:151], v[228:231], v[84:87]
	v_mfma_f32_16x16x32_bf16 v[16:19], v[156:159], v[228:231], v[16:19]
	v_mfma_f32_16x16x32_bf16 v[76:79], v[148:151], v[236:239], v[76:79]
	v_mfma_f32_16x16x32_bf16 v[28:31], v[156:159], v[236:239], v[28:31]
	v_mfma_f32_16x16x32_bf16 v[64:67], v[148:151], v[244:247], v[64:67]
	v_mfma_f32_16x16x32_bf16 v[36:39], v[156:159], v[244:247], v[36:39]
	s_add_i32 s92, s92, 2
	s_add_u32 s6, s6, 0x100
	s_addc_u32 s7, s7, 0
	s_add_u32 s53, s53, 0x100
	s_addc_u32 s55, s55, 0
	s_cmp_gt_u32 s92, 13
	s_setprio 0
	s_barrier
	s_cbranch_scc0 .LBB0_981
	s_and_b64 vcc, exec, s[46:47]
	s_cbranch_vccz .LBB0_984
	s_barrier

.LBB0_1140:
	ds_read_b128 v[144:147], v160
	ds_read_b128 v[164:167], v160 offset:1024
	ds_read_b128 v[168:171], v160 offset:2048
	ds_read_b128 v[172:175], v160 offset:3072
	ds_read_b128 v[176:179], v161
	ds_read_b128 v[182:185], v161 offset:1024
	ds_read_b128 v[186:189], v161 offset:2048
	ds_read_b128 v[190:193], v161 offset:3072
	s_add_u32 s34, s30, 0xfff40080
	s_addc_u32 s35, s31, -1
	s_cmp_eq_u32 s57, 44
	s_cselect_b32 s37, s7, s35
	s_cselect_b32 s36, s6, s34
	s_cselect_b32 s35, s29, s56
	s_cselect_b32 s34, s28, s55
	v_lshl_add_u64 v[228:229], s[30:31], 0, v[136:137]
	s_add_i32 m0, s14, 0xc000
	ds_read_b128 v[194:197], v162
	ds_read_b128 v[198:201], v162 offset:1024
	ds_read_b128 v[202:205], v162 offset:2048
	ds_read_b128 v[206:209], v162 offset:3072
	ds_read_b128 v[212:215], v162 offset:4096
	ds_read_b128 v[216:219], v162 offset:5120
	ds_read_b128 v[220:223], v162 offset:6144
	ds_read_b128 v[224:227], v162 offset:7168
	global_load_lds_dwordx4 v[228:229], off
	v_lshl_add_u64 v[228:229], s[30:31], 0, v[138:139]
	s_add_i32 m0, s14, 0xe000
	s_nop 0
	global_load_lds_dwordx4 v[228:229], off
	s_waitcnt vmcnt(8)
	s_waitcnt lgkmcnt(0)
	s_barrier
	s_setprio 1
	s_waitcnt lgkmcnt(0)
	v_mfma_f32_16x16x32_bf16 v[124:127], v[144:147], v[194:197], v[124:127]
	v_mfma_f32_16x16x32_bf16 v[120:123], v[168:171], v[194:197], v[120:123]
	v_mfma_f32_16x16x32_bf16 v[108:111], v[144:147], v[202:205], v[108:111]
	v_mfma_f32_16x16x32_bf16 v[104:107], v[168:171], v[202:205], v[104:107]
	v_mfma_f32_16x16x32_bf16 v[92:95], v[144:147], v[212:215], v[92:95]
	v_mfma_f32_16x16x32_bf16 v[88:91], v[168:171], v[212:215], v[88:91]
	v_mfma_f32_16x16x32_bf16 v[76:79], v[144:147], v[220:223], v[76:79]
	v_mfma_f32_16x16x32_bf16 v[72:75], v[168:171], v[220:223], v[72:75]
	v_mfma_f32_16x16x32_bf16 v[124:127], v[164:167], v[198:201], v[124:127]
	v_mfma_f32_16x16x32_bf16 v[120:123], v[172:175], v[198:201], v[120:123]
	v_mfma_f32_16x16x32_bf16 v[108:111], v[164:167], v[206:209], v[108:111]
	v_mfma_f32_16x16x32_bf16 v[104:107], v[172:175], v[206:209], v[104:107]
	v_mfma_f32_16x16x32_bf16 v[92:95], v[164:167], v[216:219], v[92:95]
	v_mfma_f32_16x16x32_bf16 v[88:91], v[172:175], v[216:219], v[88:91]
	v_mfma_f32_16x16x32_bf16 v[76:79], v[164:167], v[224:227], v[76:79]
	v_mfma_f32_16x16x32_bf16 v[72:75], v[172:175], v[224:227], v[72:75]
	s_setprio 0
	s_setprio 1
	v_mfma_f32_16x16x32_bf16 v[116:119], v[176:179], v[194:197], v[116:119]
	v_mfma_f32_16x16x32_bf16 v[112:115], v[186:189], v[194:197], v[112:115]
	v_mfma_f32_16x16x32_bf16 v[100:103], v[176:179], v[202:205], v[100:103]
	v_mfma_f32_16x16x32_bf16 v[96:99], v[186:189], v[202:205], v[96:99]
	v_mfma_f32_16x16x32_bf16 v[84:87], v[176:179], v[212:215], v[84:87]
	v_mfma_f32_16x16x32_bf16 v[80:83], v[186:189], v[212:215], v[80:83]
	v_mfma_f32_16x16x32_bf16 v[68:71], v[176:179], v[220:223], v[68:71]
	v_mfma_f32_16x16x32_bf16 v[64:67], v[186:189], v[220:223], v[64:67]
	v_mfma_f32_16x16x32_bf16 v[116:119], v[182:185], v[198:201], v[116:119]
	v_mfma_f32_16x16x32_bf16 v[112:115], v[190:193], v[198:201], v[112:115]
	v_mfma_f32_16x16x32_bf16 v[100:103], v[182:185], v[206:209], v[100:103]
	v_mfma_f32_16x16x32_bf16 v[96:99], v[190:193], v[206:209], v[96:99]
	v_mfma_f32_16x16x32_bf16 v[84:87], v[182:185], v[216:219], v[84:87]
	v_mfma_f32_16x16x32_bf16 v[80:83], v[190:193], v[216:219], v[80:83]
	v_mfma_f32_16x16x32_bf16 v[68:71], v[182:185], v[224:227], v[68:71]
	v_mfma_f32_16x16x32_bf16 v[64:67], v[190:193], v[224:227], v[64:67]
	s_setprio 0
	s_barrier
	s_add_i32 s58, s49, s11
	v_lshl_add_u64 v[228:229], s[34:35], 0, v[130:131]
	s_mov_b32 m0, s58
	ds_read_b128 v[194:197], v162 offset:16384
	ds_read_b128 v[198:201], v162 offset:17408
	ds_read_b128 v[202:205], v162 offset:18432
	ds_read_b128 v[206:209], v162 offset:19456
	ds_read_b128 v[212:215], v162 offset:20480
	ds_read_b128 v[216:219], v162 offset:21504
	ds_read_b128 v[220:223], v162 offset:22528
	ds_read_b128 v[224:227], v162 offset:23552
	global_load_lds_dwordx4 v[228:229], off
	s_add_i32 m0, s58, 0x2000
	s_add_u32 s58, s34, 0xc0000
	v_lshl_add_u64 v[230:231], s[34:35], 0, v[134:135]
	s_addc_u32 s59, s35, 0
	s_add_i32 s60, s50, s11
	global_load_lds_dwordx4 v[230:231], off
	v_lshl_add_u64 v[232:233], s[58:59], 0, v[130:131]
	s_mov_b32 m0, s60
	v_lshl_add_u64 v[234:235], s[36:37], 0, v[132:133]
	global_load_lds_dwordx4 v[232:233], off
	v_lshl_add_u64 v[232:233], s[58:59], 0, v[134:135]
	s_add_i32 m0, s60, 0x2000
	s_nop 0
	global_load_lds_dwordx4 v[232:233], off
	v_lshl_add_u64 v[232:233], s[36:37], 0, v[128:129]
	s_mov_b32 m0, s14
	s_nop 0
	global_load_lds_dwordx4 v[232:233], off
	s_mov_b32 m0, s15
	s_nop 0
	global_load_lds_dwordx4 v[234:235], off
	s_waitcnt vmcnt(8)
	s_waitcnt lgkmcnt(0)
	s_barrier
	s_setprio 1
	s_waitcnt lgkmcnt(0)
	v_mfma_f32_16x16x32_bf16 v[60:63], v[144:147], v[194:197], v[60:63]
	v_mfma_f32_16x16x32_bf16 v[56:59], v[168:171], v[194:197], v[56:59]
	v_mfma_f32_16x16x32_bf16 v[44:47], v[144:147], v[202:205], v[44:47]
	v_mfma_f32_16x16x32_bf16 v[40:43], v[168:171], v[202:205], v[40:43]
	v_mfma_f32_16x16x32_bf16 v[28:31], v[144:147], v[212:215], v[28:31]
	v_mfma_f32_16x16x32_bf16 v[24:27], v[168:171], v[212:215], v[24:27]
	v_mfma_f32_16x16x32_bf16 v[12:15], v[144:147], v[220:223], v[12:15]
	v_mfma_f32_16x16x32_bf16 v[8:11], v[168:171], v[220:223], v[8:11]
	v_mfma_f32_16x16x32_bf16 v[60:63], v[164:167], v[198:201], v[60:63]
	v_mfma_f32_16x16x32_bf16 v[56:59], v[172:175], v[198:201], v[56:59]
	v_mfma_f32_16x16x32_bf16 v[44:47], v[164:167], v[206:209], v[44:47]
	v_mfma_f32_16x16x32_bf16 v[40:43], v[172:175], v[206:209], v[40:43]
	v_mfma_f32_16x16x32_bf16 v[28:31], v[164:167], v[216:219], v[28:31]
	v_mfma_f32_16x16x32_bf16 v[24:27], v[172:175], v[216:219], v[24:27]
	v_mfma_f32_16x16x32_bf16 v[12:15], v[164:167], v[224:227], v[12:15]
	v_mfma_f32_16x16x32_bf16 v[8:11], v[172:175], v[224:227], v[8:11]
	s_setprio 0
	s_setprio 1
	v_mfma_f32_16x16x32_bf16 v[52:55], v[176:179], v[194:197], v[52:55]
	v_mfma_f32_16x16x32_bf16 v[48:51], v[186:189], v[194:197], v[48:51]
	v_mfma_f32_16x16x32_bf16 v[36:39], v[176:179], v[202:205], v[36:39]
	v_mfma_f32_16x16x32_bf16 v[32:35], v[186:189], v[202:205], v[32:35]
	v_mfma_f32_16x16x32_bf16 v[20:23], v[176:179], v[212:215], v[20:23]
	v_mfma_f32_16x16x32_bf16 v[16:19], v[186:189], v[212:215], v[16:19]
	v_mfma_f32_16x16x32_bf16 v[4:7], v[176:179], v[220:223], v[4:7]
	v_mfma_f32_16x16x32_bf16 v[0:3], v[186:189], v[220:223], v[0:3]
	v_mfma_f32_16x16x32_bf16 v[52:55], v[182:185], v[198:201], v[52:55]
	v_mfma_f32_16x16x32_bf16 v[48:51], v[190:193], v[198:201], v[48:51]
	v_mfma_f32_16x16x32_bf16 v[36:39], v[182:185], v[206:209], v[36:39]
	v_mfma_f32_16x16x32_bf16 v[32:35], v[190:193], v[206:209], v[32:35]
	v_mfma_f32_16x16x32_bf16 v[20:23], v[182:185], v[216:219], v[20:23]
	v_mfma_f32_16x16x32_bf16 v[16:19], v[190:193], v[216:219], v[16:19]
	v_mfma_f32_16x16x32_bf16 v[4:7], v[182:185], v[224:227], v[4:7]
	v_mfma_f32_16x16x32_bf16 v[0:3], v[190:193], v[224:227], v[0:3]
	s_setprio 0
	s_barrier
	s_add_i32 s58, 0, 0x18000
	s_add_i32 s59, 0, 0x1c000
	v_add_u32_e32 v172, s58, v158
	v_add_u32_e32 v180, s59, v158
	ds_read_b128 v[144:147], v172
	ds_read_b128 v[164:167], v172 offset:1024
	ds_read_b128 v[168:171], v172 offset:2048
	ds_read_b128 v[172:175], v172 offset:3072
	ds_read_b128 v[176:179], v180
	ds_read_b128 v[182:185], v180 offset:1024
	ds_read_b128 v[186:189], v180 offset:2048
	ds_read_b128 v[190:193], v180 offset:3072
	s_add_u32 s36, s36, 0xc0000
	s_addc_u32 s37, s37, 0
	s_mov_b32 m0, s38
	v_lshl_add_u64 v[236:237], s[36:37], 0, v[128:129]
	ds_read_b128 v[194:197], v162 offset:32768
	ds_read_b128 v[198:201], v162 offset:33792
	ds_read_b128 v[202:205], v162 offset:34816
	ds_read_b128 v[206:209], v162 offset:35840
	ds_read_b128 v[212:215], v162 offset:36864
	ds_read_b128 v[216:219], v162 offset:37888
	ds_read_b128 v[220:223], v162 offset:38912
	ds_read_b128 v[224:227], v162 offset:39936
	global_load_lds_dwordx4 v[236:237], off
	v_lshl_add_u64 v[236:237], s[36:37], 0, v[132:133]
	s_mov_b32 m0, s39
	s_nop 0
	global_load_lds_dwordx4 v[236:237], off
	s_waitcnt vmcnt(8)
	s_waitcnt lgkmcnt(0)
	s_barrier
	s_setprio 1
	s_waitcnt lgkmcnt(0)
	v_mfma_f32_16x16x32_bf16 v[124:127], v[144:147], v[194:197], v[124:127]
	v_mfma_f32_16x16x32_bf16 v[120:123], v[168:171], v[194:197], v[120:123]
	v_mfma_f32_16x16x32_bf16 v[108:111], v[144:147], v[202:205], v[108:111]
	v_mfma_f32_16x16x32_bf16 v[104:107], v[168:171], v[202:205], v[104:107]
	v_mfma_f32_16x16x32_bf16 v[92:95], v[144:147], v[212:215], v[92:95]
	v_mfma_f32_16x16x32_bf16 v[88:91], v[168:171], v[212:215], v[88:91]
	v_mfma_f32_16x16x32_bf16 v[76:79], v[144:147], v[220:223], v[76:79]
	v_mfma_f32_16x16x32_bf16 v[72:75], v[168:171], v[220:223], v[72:75]
	v_mfma_f32_16x16x32_bf16 v[124:127], v[164:167], v[198:201], v[124:127]
	v_mfma_f32_16x16x32_bf16 v[120:123], v[172:175], v[198:201], v[120:123]
	v_mfma_f32_16x16x32_bf16 v[108:111], v[164:167], v[206:209], v[108:111]
	v_mfma_f32_16x16x32_bf16 v[104:107], v[172:175], v[206:209], v[104:107]
	v_mfma_f32_16x16x32_bf16 v[92:95], v[164:167], v[216:219], v[92:95]
	v_mfma_f32_16x16x32_bf16 v[88:91], v[172:175], v[216:219], v[88:91]
	v_mfma_f32_16x16x32_bf16 v[76:79], v[164:167], v[224:227], v[76:79]
	v_mfma_f32_16x16x32_bf16 v[72:75], v[172:175], v[224:227], v[72:75]
	s_setprio 0
	s_setprio 1
	v_mfma_f32_16x16x32_bf16 v[116:119], v[176:179], v[194:197], v[116:119]
	v_mfma_f32_16x16x32_bf16 v[112:115], v[186:189], v[194:197], v[112:115]
	v_mfma_f32_16x16x32_bf16 v[100:103], v[176:179], v[202:205], v[100:103]
	v_mfma_f32_16x16x32_bf16 v[96:99], v[186:189], v[202:205], v[96:99]
	v_mfma_f32_16x16x32_bf16 v[84:87], v[176:179], v[212:215], v[84:87]
	v_mfma_f32_16x16x32_bf16 v[80:83], v[186:189], v[212:215], v[80:83]
	v_mfma_f32_16x16x32_bf16 v[68:71], v[176:179], v[220:223], v[68:71]
	v_mfma_f32_16x16x32_bf16 v[64:67], v[186:189], v[220:223], v[64:67]
	v_mfma_f32_16x16x32_bf16 v[116:119], v[182:185], v[198:201], v[116:119]
	v_mfma_f32_16x16x32_bf16 v[112:115], v[190:193], v[198:201], v[112:115]
	v_mfma_f32_16x16x32_bf16 v[100:103], v[182:185], v[206:209], v[100:103]
	v_mfma_f32_16x16x32_bf16 v[96:99], v[190:193], v[206:209], v[96:99]
	v_mfma_f32_16x16x32_bf16 v[84:87], v[182:185], v[216:219], v[84:87]
	v_mfma_f32_16x16x32_bf16 v[80:83], v[190:193], v[216:219], v[80:83]
	v_mfma_f32_16x16x32_bf16 v[68:71], v[182:185], v[224:227], v[68:71]
	v_mfma_f32_16x16x32_bf16 v[64:67], v[190:193], v[224:227], v[64:67]
	s_setprio 0
	s_barrier
	s_add_i32 s36, s58, s11
	v_lshl_add_u64 v[228:229], v[228:229], 0, s[24:25]
	s_mov_b32 m0, s36
	ds_read_b128 v[194:197], v162 offset:49152
	ds_read_b128 v[198:201], v162 offset:50176
	ds_read_b128 v[202:205], v162 offset:51200
	ds_read_b128 v[206:209], v162 offset:52224
	ds_read_b128 v[212:215], v162 offset:53248
	ds_read_b128 v[216:219], v162 offset:54272
	ds_read_b128 v[220:223], v162 offset:55296
	ds_read_b128 v[224:227], v162 offset:56320
	global_load_lds_dwordx4 v[228:229], off
	s_add_i32 m0, s36, 0x2000
	s_add_u32 s34, s34, 0xc0080
	v_lshl_add_u64 v[228:229], v[230:231], 0, s[24:25]
	s_addc_u32 s35, s35, 0
	s_add_i32 s36, s59, s11
	global_load_lds_dwordx4 v[228:229], off
	v_lshl_add_u64 v[228:229], s[34:35], 0, v[130:131]
	s_mov_b32 m0, s36
	s_nop 0
	global_load_lds_dwordx4 v[228:229], off
	v_lshl_add_u64 v[228:229], s[34:35], 0, v[134:135]
	s_add_i32 m0, s36, 0x2000
	s_nop 0
	global_load_lds_dwordx4 v[228:229], off
	v_lshl_add_u64 v[228:229], v[232:233], 0, s[24:25]
	s_mov_b32 m0, s45
	s_nop 0
	global_load_lds_dwordx4 v[228:229], off
	v_lshl_add_u64 v[228:229], v[234:235], 0, s[24:25]
	s_mov_b32 m0, s46
	s_nop 0
	global_load_lds_dwordx4 v[228:229], off
	s_waitcnt vmcnt(8)
	s_waitcnt lgkmcnt(0)
	s_barrier
	s_setprio 1
	s_waitcnt lgkmcnt(0)
	v_mfma_f32_16x16x32_bf16 v[60:63], v[144:147], v[194:197], v[60:63]
	v_mfma_f32_16x16x32_bf16 v[56:59], v[168:171], v[194:197], v[56:59]
	v_mfma_f32_16x16x32_bf16 v[44:47], v[144:147], v[202:205], v[44:47]
	v_mfma_f32_16x16x32_bf16 v[40:43], v[168:171], v[202:205], v[40:43]
	v_mfma_f32_16x16x32_bf16 v[28:31], v[144:147], v[212:215], v[28:31]
	v_mfma_f32_16x16x32_bf16 v[24:27], v[168:171], v[212:215], v[24:27]
	v_mfma_f32_16x16x32_bf16 v[12:15], v[144:147], v[220:223], v[12:15]
	v_mfma_f32_16x16x32_bf16 v[8:11], v[168:171], v[220:223], v[8:11]
	v_mfma_f32_16x16x32_bf16 v[60:63], v[164:167], v[198:201], v[60:63]
	v_mfma_f32_16x16x32_bf16 v[56:59], v[172:175], v[198:201], v[56:59]
	v_mfma_f32_16x16x32_bf16 v[44:47], v[164:167], v[206:209], v[44:47]
	v_mfma_f32_16x16x32_bf16 v[40:43], v[172:175], v[206:209], v[40:43]
	v_mfma_f32_16x16x32_bf16 v[28:31], v[164:167], v[216:219], v[28:31]
	v_mfma_f32_16x16x32_bf16 v[24:27], v[172:175], v[216:219], v[24:27]
	v_mfma_f32_16x16x32_bf16 v[12:15], v[164:167], v[224:227], v[12:15]
	v_mfma_f32_16x16x32_bf16 v[8:11], v[172:175], v[224:227], v[8:11]
	s_setprio 0
	s_setprio 1
	v_mfma_f32_16x16x32_bf16 v[52:55], v[176:179], v[194:197], v[52:55]
	v_mfma_f32_16x16x32_bf16 v[48:51], v[186:189], v[194:197], v[48:51]
	v_mfma_f32_16x16x32_bf16 v[36:39], v[176:179], v[202:205], v[36:39]
	v_mfma_f32_16x16x32_bf16 v[32:35], v[186:189], v[202:205], v[32:35]
	v_mfma_f32_16x16x32_bf16 v[20:23], v[176:179], v[212:215], v[20:23]
	v_mfma_f32_16x16x32_bf16 v[16:19], v[186:189], v[212:215], v[16:19]
	v_mfma_f32_16x16x32_bf16 v[4:7], v[176:179], v[220:223], v[4:7]
	v_mfma_f32_16x16x32_bf16 v[0:3], v[186:189], v[220:223], v[0:3]
	v_mfma_f32_16x16x32_bf16 v[52:55], v[182:185], v[198:201], v[52:55]
	v_mfma_f32_16x16x32_bf16 v[48:51], v[190:193], v[198:201], v[48:51]
	v_mfma_f32_16x16x32_bf16 v[36:39], v[182:185], v[206:209], v[36:39]
	v_mfma_f32_16x16x32_bf16 v[32:35], v[190:193], v[206:209], v[32:35]
	v_mfma_f32_16x16x32_bf16 v[20:23], v[182:185], v[216:219], v[20:23]
	v_mfma_f32_16x16x32_bf16 v[16:19], v[190:193], v[216:219], v[16:19]
	v_mfma_f32_16x16x32_bf16 v[4:7], v[182:185], v[224:227], v[4:7]
	v_mfma_f32_16x16x32_bf16 v[0:3], v[190:193], v[224:227], v[0:3]
	s_add_i32 s57, s57, 2
	s_add_u32 s30, s30, 0x100
	s_addc_u32 s31, s31, 0
	s_add_u32 s55, s55, 0x100
	s_addc_u32 s56, s56, 0
	s_cmp_gt_u32 s57, 45
	s_setprio 0
	s_barrier
	s_cbranch_scc0 .LBB0_1140
	s_and_b64 vcc, exec, s[26:27]
	s_cbranch_vccz .LBB0_1143
	s_barrier

.LBB0_1261:
	ds_read_b128 v[144:147], v155
	ds_read_b128 v[148:151], v155 offset:1024
	ds_read_b128 v[160:163], v155 offset:2048
	ds_read_b128 v[164:167], v155 offset:3072
	ds_read_b128 v[168:171], v156
	ds_read_b128 v[172:175], v156 offset:1024
	ds_read_b128 v[176:179], v156 offset:2048
	ds_read_b128 v[182:185], v156 offset:3072
	s_add_u32 s38, s36, 0xfffc0080
	s_addc_u32 s39, s37, -1
	s_cmp_eq_u32 s60, 12
	s_cselect_b32 s45, s14, s39
	s_cselect_b32 s44, s15, s38
	s_cselect_b32 s39, s25, s59
	s_cselect_b32 s38, s27, s29
	v_lshl_add_u64 v[220:221], s[36:37], 0, v[136:137]
	s_add_i32 m0, s46, 0xc000
	ds_read_b128 v[186:189], v157
	ds_read_b128 v[190:193], v157 offset:1024
	ds_read_b128 v[194:197], v157 offset:2048
	ds_read_b128 v[198:201], v157 offset:3072
	ds_read_b128 v[202:205], v157 offset:4096
	ds_read_b128 v[206:209], v157 offset:5120
	ds_read_b128 v[212:215], v157 offset:6144
	ds_read_b128 v[216:219], v157 offset:7168
	global_load_lds_dwordx4 v[220:221], off
	v_lshl_add_u64 v[220:221], s[36:37], 0, v[138:139]
	s_add_i32 m0, s46, 0xe000
	s_nop 0
	global_load_lds_dwordx4 v[220:221], off
	s_waitcnt vmcnt(8)
	s_waitcnt lgkmcnt(0)
	s_barrier
	s_setprio 1
	s_waitcnt lgkmcnt(0)
	v_mfma_f32_16x16x32_bf16 v[124:127], v[144:147], v[186:189], v[124:127]
	v_mfma_f32_16x16x32_bf16 v[120:123], v[160:163], v[186:189], v[120:123]
	v_mfma_f32_16x16x32_bf16 v[108:111], v[144:147], v[194:197], v[108:111]
	v_mfma_f32_16x16x32_bf16 v[104:107], v[160:163], v[194:197], v[104:107]
	v_mfma_f32_16x16x32_bf16 v[92:95], v[144:147], v[202:205], v[92:95]
	v_mfma_f32_16x16x32_bf16 v[88:91], v[160:163], v[202:205], v[88:91]
	v_mfma_f32_16x16x32_bf16 v[76:79], v[144:147], v[212:215], v[76:79]
	v_mfma_f32_16x16x32_bf16 v[72:75], v[160:163], v[212:215], v[72:75]
	v_mfma_f32_16x16x32_bf16 v[124:127], v[148:151], v[190:193], v[124:127]
	v_mfma_f32_16x16x32_bf16 v[120:123], v[164:167], v[190:193], v[120:123]
	v_mfma_f32_16x16x32_bf16 v[108:111], v[148:151], v[198:201], v[108:111]
	v_mfma_f32_16x16x32_bf16 v[104:107], v[164:167], v[198:201], v[104:107]
	v_mfma_f32_16x16x32_bf16 v[92:95], v[148:151], v[206:209], v[92:95]
	v_mfma_f32_16x16x32_bf16 v[88:91], v[164:167], v[206:209], v[88:91]
	v_mfma_f32_16x16x32_bf16 v[76:79], v[148:151], v[216:219], v[76:79]
	v_mfma_f32_16x16x32_bf16 v[72:75], v[164:167], v[216:219], v[72:75]
	s_setprio 0
	s_setprio 1
	v_mfma_f32_16x16x32_bf16 v[116:119], v[168:171], v[186:189], v[116:119]
	v_mfma_f32_16x16x32_bf16 v[112:115], v[176:179], v[186:189], v[112:115]
	v_mfma_f32_16x16x32_bf16 v[100:103], v[168:171], v[194:197], v[100:103]
	v_mfma_f32_16x16x32_bf16 v[96:99], v[176:179], v[194:197], v[96:99]
	v_mfma_f32_16x16x32_bf16 v[84:87], v[168:171], v[202:205], v[84:87]
	v_mfma_f32_16x16x32_bf16 v[80:83], v[176:179], v[202:205], v[80:83]
	v_mfma_f32_16x16x32_bf16 v[68:71], v[168:171], v[212:215], v[68:71]
	v_mfma_f32_16x16x32_bf16 v[64:67], v[176:179], v[212:215], v[64:67]
	v_mfma_f32_16x16x32_bf16 v[116:119], v[172:175], v[190:193], v[116:119]
	v_mfma_f32_16x16x32_bf16 v[112:115], v[182:185], v[190:193], v[112:115]
	v_mfma_f32_16x16x32_bf16 v[100:103], v[172:175], v[198:201], v[100:103]
	v_mfma_f32_16x16x32_bf16 v[96:99], v[182:185], v[198:201], v[96:99]
	v_mfma_f32_16x16x32_bf16 v[84:87], v[172:175], v[206:209], v[84:87]
	v_mfma_f32_16x16x32_bf16 v[80:83], v[182:185], v[206:209], v[80:83]
	v_mfma_f32_16x16x32_bf16 v[68:71], v[172:175], v[216:219], v[68:71]
	v_mfma_f32_16x16x32_bf16 v[64:67], v[182:185], v[216:219], v[64:67]
	s_setprio 0
	s_barrier
	s_add_i32 s61, s55, s11
	v_lshl_add_u64 v[220:221], s[38:39], 0, v[130:131]
	s_mov_b32 m0, s61
	ds_read_b128 v[186:189], v157 offset:16384
	ds_read_b128 v[190:193], v157 offset:17408
	ds_read_b128 v[194:197], v157 offset:18432
	ds_read_b128 v[198:201], v157 offset:19456
	ds_read_b128 v[202:205], v157 offset:20480
	ds_read_b128 v[206:209], v157 offset:21504
	ds_read_b128 v[212:215], v157 offset:22528
	ds_read_b128 v[216:219], v157 offset:23552
	global_load_lds_dwordx4 v[220:221], off
	s_add_i32 m0, s61, 0x2000
	s_add_u32 s62, s38, 0x40000
	v_lshl_add_u64 v[222:223], s[38:39], 0, v[134:135]
	s_addc_u32 s63, s39, 0
	s_add_i32 s61, s56, s11
	global_load_lds_dwordx4 v[222:223], off
	v_lshl_add_u64 v[224:225], s[62:63], 0, v[130:131]
	s_mov_b32 m0, s61
	v_lshl_add_u64 v[226:227], s[44:45], 0, v[132:133]
	global_load_lds_dwordx4 v[224:225], off
	v_lshl_add_u64 v[224:225], s[62:63], 0, v[134:135]
	s_add_i32 m0, s61, 0x2000
	s_nop 0
	global_load_lds_dwordx4 v[224:225], off
	v_lshl_add_u64 v[224:225], s[44:45], 0, v[128:129]
	s_mov_b32 m0, s46
	s_nop 0
	global_load_lds_dwordx4 v[224:225], off
	s_mov_b32 m0, s47
	s_nop 0
	global_load_lds_dwordx4 v[226:227], off
	s_waitcnt vmcnt(8)
	s_waitcnt lgkmcnt(0)
	s_barrier
	s_setprio 1
	s_waitcnt lgkmcnt(0)
	v_mfma_f32_16x16x32_bf16 v[60:63], v[144:147], v[186:189], v[60:63]
	v_mfma_f32_16x16x32_bf16 v[56:59], v[160:163], v[186:189], v[56:59]
	v_mfma_f32_16x16x32_bf16 v[44:47], v[144:147], v[194:197], v[44:47]
	v_mfma_f32_16x16x32_bf16 v[40:43], v[160:163], v[194:197], v[40:43]
	v_mfma_f32_16x16x32_bf16 v[28:31], v[144:147], v[202:205], v[28:31]
	v_mfma_f32_16x16x32_bf16 v[24:27], v[160:163], v[202:205], v[24:27]
	v_mfma_f32_16x16x32_bf16 v[12:15], v[144:147], v[212:215], v[12:15]
	v_mfma_f32_16x16x32_bf16 v[8:11], v[160:163], v[212:215], v[8:11]
	v_mfma_f32_16x16x32_bf16 v[60:63], v[148:151], v[190:193], v[60:63]
	v_mfma_f32_16x16x32_bf16 v[56:59], v[164:167], v[190:193], v[56:59]
	v_mfma_f32_16x16x32_bf16 v[44:47], v[148:151], v[198:201], v[44:47]
	v_mfma_f32_16x16x32_bf16 v[40:43], v[164:167], v[198:201], v[40:43]
	v_mfma_f32_16x16x32_bf16 v[28:31], v[148:151], v[206:209], v[28:31]
	v_mfma_f32_16x16x32_bf16 v[24:27], v[164:167], v[206:209], v[24:27]
	v_mfma_f32_16x16x32_bf16 v[12:15], v[148:151], v[216:219], v[12:15]
	v_mfma_f32_16x16x32_bf16 v[8:11], v[164:167], v[216:219], v[8:11]
	s_setprio 0
	s_setprio 1
	v_mfma_f32_16x16x32_bf16 v[52:55], v[168:171], v[186:189], v[52:55]
	v_mfma_f32_16x16x32_bf16 v[48:51], v[176:179], v[186:189], v[48:51]
	v_mfma_f32_16x16x32_bf16 v[36:39], v[168:171], v[194:197], v[36:39]
	v_mfma_f32_16x16x32_bf16 v[32:35], v[176:179], v[194:197], v[32:35]
	v_mfma_f32_16x16x32_bf16 v[20:23], v[168:171], v[202:205], v[20:23]
	v_mfma_f32_16x16x32_bf16 v[16:19], v[176:179], v[202:205], v[16:19]
	v_mfma_f32_16x16x32_bf16 v[4:7], v[168:171], v[212:215], v[4:7]
	v_mfma_f32_16x16x32_bf16 v[0:3], v[176:179], v[212:215], v[0:3]
	v_mfma_f32_16x16x32_bf16 v[52:55], v[172:175], v[190:193], v[52:55]
	v_mfma_f32_16x16x32_bf16 v[48:51], v[182:185], v[190:193], v[48:51]
	v_mfma_f32_16x16x32_bf16 v[36:39], v[172:175], v[198:201], v[36:39]
	v_mfma_f32_16x16x32_bf16 v[32:35], v[182:185], v[198:201], v[32:35]
	v_mfma_f32_16x16x32_bf16 v[20:23], v[172:175], v[206:209], v[20:23]
	v_mfma_f32_16x16x32_bf16 v[16:19], v[182:185], v[206:209], v[16:19]
	v_mfma_f32_16x16x32_bf16 v[4:7], v[172:175], v[216:219], v[4:7]
	v_mfma_f32_16x16x32_bf16 v[0:3], v[182:185], v[216:219], v[0:3]
	s_setprio 0
	s_barrier
	s_add_i32 s61, 0, 0x18000
	s_add_i32 s62, 0, 0x1c000
	v_add_u32_e32 v164, s61, v153
	v_add_u32_e32 v180, s62, v153
	ds_read_b128 v[144:147], v164
	ds_read_b128 v[148:151], v164 offset:1024
	ds_read_b128 v[160:163], v164 offset:2048
	ds_read_b128 v[164:167], v164 offset:3072
	ds_read_b128 v[168:171], v180
	ds_read_b128 v[172:175], v180 offset:1024
	ds_read_b128 v[176:179], v180 offset:2048
	ds_read_b128 v[182:185], v180 offset:3072
	s_add_u32 s44, s44, 0x40000
	s_addc_u32 s45, s45, 0
	s_mov_b32 m0, s48
	v_lshl_add_u64 v[228:229], s[44:45], 0, v[128:129]
	ds_read_b128 v[186:189], v157 offset:32768
	ds_read_b128 v[190:193], v157 offset:33792
	ds_read_b128 v[194:197], v157 offset:34816
	ds_read_b128 v[198:201], v157 offset:35840
	ds_read_b128 v[202:205], v157 offset:36864
	ds_read_b128 v[206:209], v157 offset:37888
	ds_read_b128 v[212:215], v157 offset:38912
	ds_read_b128 v[216:219], v157 offset:39936
	global_load_lds_dwordx4 v[228:229], off
	v_lshl_add_u64 v[228:229], s[44:45], 0, v[132:133]
	s_mov_b32 m0, s49
	s_nop 0
	global_load_lds_dwordx4 v[228:229], off
	s_waitcnt vmcnt(8)
	s_waitcnt lgkmcnt(0)
	s_barrier
	s_setprio 1
	s_waitcnt lgkmcnt(0)
	v_mfma_f32_16x16x32_bf16 v[124:127], v[144:147], v[186:189], v[124:127]
	v_mfma_f32_16x16x32_bf16 v[120:123], v[160:163], v[186:189], v[120:123]
	v_mfma_f32_16x16x32_bf16 v[108:111], v[144:147], v[194:197], v[108:111]
	v_mfma_f32_16x16x32_bf16 v[104:107], v[160:163], v[194:197], v[104:107]
	v_mfma_f32_16x16x32_bf16 v[92:95], v[144:147], v[202:205], v[92:95]
	v_mfma_f32_16x16x32_bf16 v[88:91], v[160:163], v[202:205], v[88:91]
	v_mfma_f32_16x16x32_bf16 v[76:79], v[144:147], v[212:215], v[76:79]
	v_mfma_f32_16x16x32_bf16 v[72:75], v[160:163], v[212:215], v[72:75]
	v_mfma_f32_16x16x32_bf16 v[124:127], v[148:151], v[190:193], v[124:127]
	v_mfma_f32_16x16x32_bf16 v[120:123], v[164:167], v[190:193], v[120:123]
	v_mfma_f32_16x16x32_bf16 v[108:111], v[148:151], v[198:201], v[108:111]
	v_mfma_f32_16x16x32_bf16 v[104:107], v[164:167], v[198:201], v[104:107]
	v_mfma_f32_16x16x32_bf16 v[92:95], v[148:151], v[206:209], v[92:95]
	v_mfma_f32_16x16x32_bf16 v[88:91], v[164:167], v[206:209], v[88:91]
	v_mfma_f32_16x16x32_bf16 v[76:79], v[148:151], v[216:219], v[76:79]
	v_mfma_f32_16x16x32_bf16 v[72:75], v[164:167], v[216:219], v[72:75]
	s_setprio 0
	s_setprio 1
	v_mfma_f32_16x16x32_bf16 v[116:119], v[168:171], v[186:189], v[116:119]
	v_mfma_f32_16x16x32_bf16 v[112:115], v[176:179], v[186:189], v[112:115]
	v_mfma_f32_16x16x32_bf16 v[100:103], v[168:171], v[194:197], v[100:103]
	v_mfma_f32_16x16x32_bf16 v[96:99], v[176:179], v[194:197], v[96:99]
	v_mfma_f32_16x16x32_bf16 v[84:87], v[168:171], v[202:205], v[84:87]
	v_mfma_f32_16x16x32_bf16 v[80:83], v[176:179], v[202:205], v[80:83]
	v_mfma_f32_16x16x32_bf16 v[68:71], v[168:171], v[212:215], v[68:71]
	v_mfma_f32_16x16x32_bf16 v[64:67], v[176:179], v[212:215], v[64:67]
	v_mfma_f32_16x16x32_bf16 v[116:119], v[172:175], v[190:193], v[116:119]
	v_mfma_f32_16x16x32_bf16 v[112:115], v[182:185], v[190:193], v[112:115]
	v_mfma_f32_16x16x32_bf16 v[100:103], v[172:175], v[198:201], v[100:103]
	v_mfma_f32_16x16x32_bf16 v[96:99], v[182:185], v[198:201], v[96:99]
	v_mfma_f32_16x16x32_bf16 v[84:87], v[172:175], v[206:209], v[84:87]
	v_mfma_f32_16x16x32_bf16 v[80:83], v[182:185], v[206:209], v[80:83]
	v_mfma_f32_16x16x32_bf16 v[68:71], v[172:175], v[216:219], v[68:71]
	v_mfma_f32_16x16x32_bf16 v[64:67], v[182:185], v[216:219], v[64:67]
	s_setprio 0
	s_barrier
	s_add_i32 s44, s61, s11
	v_lshl_add_u64 v[220:221], v[220:221], 0, s[20:21]
	s_mov_b32 m0, s44
	ds_read_b128 v[186:189], v157 offset:49152
	ds_read_b128 v[190:193], v157 offset:50176
	ds_read_b128 v[194:197], v157 offset:51200
	ds_read_b128 v[198:201], v157 offset:52224
	ds_read_b128 v[202:205], v157 offset:53248
	ds_read_b128 v[206:209], v157 offset:54272
	ds_read_b128 v[212:215], v157 offset:55296
	ds_read_b128 v[216:219], v157 offset:56320
	global_load_lds_dwordx4 v[220:221], off
	s_add_i32 m0, s44, 0x2000
	s_add_u32 s38, s38, 0x40080
	v_lshl_add_u64 v[220:221], v[222:223], 0, s[20:21]
	s_addc_u32 s39, s39, 0
	s_add_i32 s44, s62, s11
	global_load_lds_dwordx4 v[220:221], off
	v_lshl_add_u64 v[220:221], s[38:39], 0, v[130:131]
	s_mov_b32 m0, s44
	s_nop 0
	global_load_lds_dwordx4 v[220:221], off
	v_lshl_add_u64 v[220:221], s[38:39], 0, v[134:135]
	s_add_i32 m0, s44, 0x2000
	s_nop 0
	global_load_lds_dwordx4 v[220:221], off
	v_lshl_add_u64 v[220:221], v[224:225], 0, s[20:21]
	s_mov_b32 m0, s51
	s_nop 0
	global_load_lds_dwordx4 v[220:221], off
	v_lshl_add_u64 v[220:221], v[226:227], 0, s[20:21]
	s_mov_b32 m0, s52
	s_nop 0
	global_load_lds_dwordx4 v[220:221], off
	s_waitcnt vmcnt(8)
	s_waitcnt lgkmcnt(0)
	s_barrier
	s_setprio 1
	s_waitcnt lgkmcnt(0)
	v_mfma_f32_16x16x32_bf16 v[60:63], v[144:147], v[186:189], v[60:63]
	v_mfma_f32_16x16x32_bf16 v[56:59], v[160:163], v[186:189], v[56:59]
	v_mfma_f32_16x16x32_bf16 v[44:47], v[144:147], v[194:197], v[44:47]
	v_mfma_f32_16x16x32_bf16 v[40:43], v[160:163], v[194:197], v[40:43]
	v_mfma_f32_16x16x32_bf16 v[28:31], v[144:147], v[202:205], v[28:31]
	v_mfma_f32_16x16x32_bf16 v[24:27], v[160:163], v[202:205], v[24:27]
	v_mfma_f32_16x16x32_bf16 v[12:15], v[144:147], v[212:215], v[12:15]
	v_mfma_f32_16x16x32_bf16 v[8:11], v[160:163], v[212:215], v[8:11]
	v_mfma_f32_16x16x32_bf16 v[60:63], v[148:151], v[190:193], v[60:63]
	v_mfma_f32_16x16x32_bf16 v[56:59], v[164:167], v[190:193], v[56:59]
	v_mfma_f32_16x16x32_bf16 v[44:47], v[148:151], v[198:201], v[44:47]
	v_mfma_f32_16x16x32_bf16 v[40:43], v[164:167], v[198:201], v[40:43]
	v_mfma_f32_16x16x32_bf16 v[28:31], v[148:151], v[206:209], v[28:31]
	v_mfma_f32_16x16x32_bf16 v[24:27], v[164:167], v[206:209], v[24:27]
	v_mfma_f32_16x16x32_bf16 v[12:15], v[148:151], v[216:219], v[12:15]
	v_mfma_f32_16x16x32_bf16 v[8:11], v[164:167], v[216:219], v[8:11]
	s_setprio 0
	s_setprio 1
	v_mfma_f32_16x16x32_bf16 v[52:55], v[168:171], v[186:189], v[52:55]
	v_mfma_f32_16x16x32_bf16 v[48:51], v[176:179], v[186:189], v[48:51]
	v_mfma_f32_16x16x32_bf16 v[36:39], v[168:171], v[194:197], v[36:39]
	v_mfma_f32_16x16x32_bf16 v[32:35], v[176:179], v[194:197], v[32:35]
	v_mfma_f32_16x16x32_bf16 v[20:23], v[168:171], v[202:205], v[20:23]
	v_mfma_f32_16x16x32_bf16 v[16:19], v[176:179], v[202:205], v[16:19]
	v_mfma_f32_16x16x32_bf16 v[4:7], v[168:171], v[212:215], v[4:7]
	v_mfma_f32_16x16x32_bf16 v[0:3], v[176:179], v[212:215], v[0:3]
	v_mfma_f32_16x16x32_bf16 v[52:55], v[172:175], v[190:193], v[52:55]
	v_mfma_f32_16x16x32_bf16 v[48:51], v[182:185], v[190:193], v[48:51]
	v_mfma_f32_16x16x32_bf16 v[36:39], v[172:175], v[198:201], v[36:39]
	v_mfma_f32_16x16x32_bf16 v[32:35], v[182:185], v[198:201], v[32:35]
	v_mfma_f32_16x16x32_bf16 v[20:23], v[172:175], v[206:209], v[20:23]
	v_mfma_f32_16x16x32_bf16 v[16:19], v[182:185], v[206:209], v[16:19]
	v_mfma_f32_16x16x32_bf16 v[4:7], v[172:175], v[216:219], v[4:7]
	v_mfma_f32_16x16x32_bf16 v[0:3], v[182:185], v[216:219], v[0:3]
	s_add_i32 s60, s60, 2
	s_add_u32 s36, s36, 0x100
	s_addc_u32 s37, s37, 0
	s_add_u32 s29, s29, 0x100
	s_addc_u32 s59, s59, 0
	s_cmp_gt_u32 s60, 13
	s_setprio 0
	s_barrier
	s_cbranch_scc0 .LBB0_1261
	s_and_b64 vcc, exec, s[22:23]
	s_cbranch_vccz .LBB0_1264
	s_barrier
